# gMLP spatial weights (prompt tiles) stored by P0 in MFMA-fragment order so each K-step fragment load is one contiguous 1 KiB per wave
# speedup vs baseline: 1.0084x; 1.0021x over previous
; __device__ __forceinline__ bf16 f2bf(float f) { return (bf16)(cvt_pk_nv(f, 0.f) & 0xffffu); }
;     __device__ __forceinline__ const float* in(int i) const { return karg_in(i); }
; __device__ __forceinline__ void p0_prologue(const Ctx& C, LAS unsigned char* lds, int wave, int lane, int tid) {
;     ...
;     for (int idx = gt; idx < 2 * 4 * 128 * 128; idx += NGT) {
;         const int s = idx & 127, t = (idx >> 7) & 127, h = (idx >> 14) & 3, mode = idx >> 16;
;         float v;
;         if (mode == 0) v = (s <= t) ? C.in(12)[((size_t)h * 128 + t) * 128 + s] : 0.f;
;         else v = ((s >> 4) == (t >> 4) && (s & 15) <= (t & 15)) ? C.in(12)[((size_t)h * 128 + (t & 15)) * 128 + (s & 15)] : 0.f;
;         C.Weff()[idx] = f2bf(v);
;     }
.LBB0_131:
	s_or_b64 exec, exec, s[16:17]
	s_mov_b64 s[0:1], s[80:81]
	s_load_dwordx2 s[0:1], s[0:1], 0x110
	v_add_u32_e32 v0, s6, v0
	v_cmp_lt_i32_e32 vcc, s10, v0
	s_or_b64 s[12:13], vcc, s[12:13]
	s_waitcnt vmcnt(0)
	v_cvt_pk_bf16_f32 v1, v1, v5
	s_waitcnt lgkmcnt(0)
	v_and_b32_e32 v46, 0x3ffff, v2
	v_and_b32_e32 v47, 0x3e00e, v46
	v_bfe_u32 v48, v46, 8, 5
	v_lshl_or_b32 v47, v48, 4, v47
	v_bfe_u32 v48, v46, 4, 1
	v_lshl_or_b32 v47, v48, 9, v47
	v_bfe_u32 v48, v46, 5, 3
	v_lshl_or_b32 v47, v48, 10, v47
	v_cmp_gt_u32_e32 vcc, 0x20000, v46
	s_nop 1
	v_cndmask_b32_e32 v46, v46, v47, vcc
	v_add_u32_e32 v46, 0x2900000, v46
	v_mov_b32_e32 v47, 0
	v_lshl_add_u64 v[6:7], s[0:1], 0, v[46:47]
	v_lshl_add_u64 v[2:3], v[2:3], 0, s[8:9]
	global_store_short v[6:7], v1, off
	s_andn2_b64 exec, exec, s[12:13]
	s_cbranch_execz .LBB0_144

; #define LAS __attribute__((address_space(3)))
;     __device__ __forceinline__ const float* in(int i) const { return karg_in(i); }
;     __device__ __forceinline__ float* out() const { return (float*)karg_in(33); }
; template <bool PASS2>
; __device__ __forceinline__ void s5_tile(const Ctx& C, int T, int sb_lo, int sb_hi, LAS unsigned char* lds, int wave, int lane) {
;     ...
; #pragma unroll
;     for (int gi = 0; gi < 4; ++gi) {
;         const int g = wave * 4 + gi;
;         if (!PASS2) { v2f* Ep = (v2f*)C.E() + ((size_t)T * NG + g) * NP + lane; *Ep = (v2f){sr[gi], si[gi]}; }
;         else if (!sample && (T & 127) == 127) { const int b = T >> 7;
;             C.out()[OFF_SRE_P + ((size_t)b * NG + g) * NP + lane] = sr[gi]; C.out()[OFF_SIM_P + ((size_t)b * NG + g) * NP + lane] = si[gi]; }
;     }
; __device__ __forceinline__ void gmlp_tile(const Ctx& C, int T, LAS unsigned char* lds, int wave, int lane, int tid) {
;     const int mode = (T == NTILE - 1) ? 1 : 0;
;     const int r0 = T * 128;
;     LAS bf16* VT = (LAS bf16*)lds;
;     LAS float* SSQ = (LAS float*)(lds + 128 * VT_STRIDE * 2);
;     const int tb = wave & 3, dh = wave >> 2, tl = lane & 31, hh = lane >> 5;
;     const int t = 32 * tb + tl;
;     unsigned outp[4][2][8]; float ssq = 0.f;
;     const bf16* zt = C.Z() + (size_t)(r0 + t) * DIN;
;     const int row = tid >> 2, q = tid & 3;
;     const bf16* vsrc = C.Z() + (size_t)(r0 + row) * DIN + 512 + q * 32;
;     const bf16* Weff = C.Weff();
;     v4u vraw[4];
; #pragma unroll
;     for (int i = 0; i < 4; ++i) vraw[i] = *(const v4u*)(vsrc + 8 * i);
; #pragma unroll
;     for (int h = 0; h < 4; ++h) {
;         bfx8 wf[8];
;         const bf16* wrow = Weff + ((size_t)(mode * 4 + h) * 128 + t) * 128 + 8 * hh;
; #pragma unroll
;         for (int ks = 0; ks < 8; ++ks) wf[ks] = *(const bfx8*)(wrow + 16 * ks);
;         v2u uw[2][4];
; #pragma unroll
;         for (int dbi = 0; dbi < 2; ++dbi)
; #pragma unroll
;             for (int rg = 0; rg < 4; ++rg) uw[dbi][rg] = *(const v2u*)(zt + h * 128 + 32 * (2 * dh + dbi) + 8 * rg + 4 * hh);
;         const float bias = C.in(13)[h * 128 + (mode ? (t & 15) : t)];
;         v4f gvv[8];
;         { const float* gvp = C.in(11) + h * 128 + q * 32;
; #pragma unroll
;           for (int i = 0; i < 8; ++i) gvv[i] = *(const v4f*)(gvp + 4 * i); }
.LBB0_599:
	s_mov_b64 s[0:1], s[80:81]
	s_load_dwordx2 s[0:1], s[0:1], 0x110
	s_lshl_b32 s28, s42, 2
	s_ashr_i32 s25, s24, 31
	s_lshl_b64 s[52:53], s[24:25], 14
	s_ashr_i32 s29, s28, 31
	s_waitcnt lgkmcnt(0)
	s_add_u32 s3, s0, s52
	s_addc_u32 s25, s1, s53
	s_lshl_b64 s[0:1], s[28:29], 9
	s_add_u32 s0, s3, s0
	s_addc_u32 s1, s25, s1
	v_lshlrev_b32_e32 v82, 3, v80
	v_lshl_add_u64 v[0:1], s[0:1], 0, v[82:83]
	v_add_co_u32_e32 v0, vcc, s35, v0
	v_pk_mov_b32 v[2:3], v[166:167], v[166:167] op_sel:[1,0]
	s_nop 0
	v_addc_co_u32_e32 v1, vcc, 0, v1, vcc
	s_mov_b64 s[0:1], s[80:81]
	global_store_dwordx2 v[0:1], v[2:3], off
	s_load_dwordx2 s[0:1], s[0:1], 0x110
	s_or_b32 s54, s28, 1
	s_ashr_i32 s55, s54, 31
	v_pk_mov_b32 v[2:3], v[164:165], v[164:165] op_sel:[1,0]
	v_mov_b32_e32 v97, v83
	s_waitcnt lgkmcnt(0)
	s_add_u32 s3, s0, s52
	s_addc_u32 s25, s1, s53
	s_lshl_b64 s[0:1], s[54:55], 9
	s_add_u32 s0, s3, s0
	s_addc_u32 s1, s25, s1
	v_lshl_add_u64 v[0:1], s[0:1], 0, v[82:83]
	v_add_co_u32_e32 v0, vcc, s35, v0
	s_mov_b64 s[0:1], s[80:81]
	s_nop 0
	v_addc_co_u32_e32 v1, vcc, 0, v1, vcc
	global_store_dwordx2 v[0:1], v[2:3], off
	s_load_dwordx2 s[0:1], s[0:1], 0x110
	s_or_b32 s54, s28, 2
	s_ashr_i32 s55, s54, 31
	v_pk_mov_b32 v[2:3], v[162:163], v[162:163] op_sel:[1,0]
	v_mov_b32_e32 v101, v83
	s_waitcnt lgkmcnt(0)
	s_add_u32 s3, s0, s52
	s_addc_u32 s25, s1, s53
	s_lshl_b64 s[0:1], s[54:55], 9
	s_add_u32 s0, s3, s0
	s_addc_u32 s1, s25, s1
	v_lshl_add_u64 v[0:1], s[0:1], 0, v[82:83]
	v_add_co_u32_e32 v0, vcc, s35, v0
	s_mov_b64 s[0:1], s[80:81]
	s_nop 0
	v_addc_co_u32_e32 v1, vcc, 0, v1, vcc
	global_store_dwordx2 v[0:1], v[2:3], off
	s_load_dwordx2 s[0:1], s[0:1], 0x110
	s_or_b32 s28, s28, 3
	s_ashr_i32 s29, s28, 31
	v_pk_mov_b32 v[2:3], v[160:161], v[160:161] op_sel:[1,0]
	v_lshlrev_b32_e32 v139, 2, v86
	s_waitcnt lgkmcnt(0)
	s_add_u32 s3, s0, s52
	s_addc_u32 s25, s1, s53
	s_lshl_b64 s[0:1], s[28:29], 9
	s_add_u32 s0, s3, s0
	s_addc_u32 s1, s25, s1
	v_lshl_add_u64 v[0:1], s[0:1], 0, v[82:83]
	v_add_co_u32_e32 v0, vcc, s35, v0
	s_mov_b64 s[0:1], s[80:81]
	s_nop 0
	v_addc_co_u32_e32 v1, vcc, 0, v1, vcc
	global_store_dwordx2 v[0:1], v[2:3], off
	s_barrier
	s_mov_b64 s[28:29], s[80:81]
	s_load_dwordx2 s[0:1], s[0:1], 0x110
	s_load_dwordx2 s[28:29], s[28:29], 0x110
	v_add_u32_e32 v2, s26, v173
	v_lshlrev_b32_e32 v82, 1, v86
	s_lshl_b32 s3, s42, 5
	s_and_b32 s3, s3, 0x60
	s_waitcnt lgkmcnt(0)
	v_mov_b64_e32 v[0:1], s[28:29]
	v_mad_i64_i32 v[0:1], s[28:29], v2, s34, v[0:1]
	v_lshl_add_u64 v[0:1], v[0:1], 0, v[82:83]
	v_add_co_u32_e32 v2, vcc, s36, v0
	s_mov_b64 s[28:29], s[80:81]
	s_nop 0
	v_addc_co_u32_e32 v3, vcc, 0, v1, vcc
	global_load_dwordx4 v[8:11], v[2:3], off offset:1024
	v_lshl_add_u64 v[108:109], v[0:1], 0, s[18:19]
	global_load_dwordx4 v[12:15], v[108:109], off offset:16
	global_load_dwordx4 v[16:19], v[108:109], off offset:32
	global_load_dwordx4 v[20:23], v[108:109], off offset:48
	v_or_b32_e32 v132, s3, v85
	v_or_b32_e32 v2, s26, v132
	s_load_dwordx2 s[26:27], s[28:29], 0x110
	v_mov_b64_e32 v[0:1], s[0:1]
	s_ashr_i32 s13, s13, 8
	v_mad_i64_i32 v[0:1], s[0:1], v2, s34, v[0:1]
	s_waitcnt lgkmcnt(0)
	v_lshl_add_u64 v[2:3], s[26:27], 0, v[96:97]
	v_lshlrev_b32_e32 v82, 8, v132
	s_lshl_b32 s26, s13, 6
	v_lshl_add_u64 v[104:105], v[2:3], 0, v[82:83]
	v_bfe_u32 v234, v81, 5, 1
	v_mul_u32_u24_e32 v234, 0x1f0, v234
	v_mul_u32_u24_e32 v235, 0xf0, v85
	v_sub_u32_e32 v234, v234, v235
	v_add_u32_e32 v234, 0xe00, v234
	v_ashrrev_i32_e32 v235, 31, v234
	v_lshl_add_u64 v[104:105], v[234:235], 0, v[104:105]
	v_lshl_add_u64 v[4:5], v[0:1], 0, v[100:101]
	v_add_co_u32_e32 v0, vcc, s37, v104
	s_ashr_i32 s27, s26, 31
	v_lshl_add_u64 v[6:7], v[104:105], 0, s[20:21]
	v_addc_co_u32_e32 v1, vcc, 0, v105, vcc
	v_lshl_add_u64 v[4:5], s[26:27], 1, v[4:5]
	global_load_dwordx4 v[64:67], v[6:7], off offset:-2560
	global_load_dwordx4 v[60:63], v[6:7], off offset:-1536
	global_load_dwordx4 v[56:59], v[6:7], off offset:-512
	global_load_dwordx4 v[48:51], v[6:7], off offset:512
	global_load_dwordx4 v[44:47], v[6:7], off offset:1536
	global_load_dwordx4 v[36:39], v[6:7], off offset:2560
	s_nop 0
	global_load_dwordx4 v[0:3], v[0:1], off offset:-3584
	s_nop 0
	global_load_dwordx4 v[28:31], v[6:7], off offset:3584
	v_add_co_u32_e32 v6, vcc, s36, v4
	v_lshl_add_u64 v[106:107], v[4:5], 0, s[22:23]
	s_nop 0
	v_addc_co_u32_e32 v7, vcc, 0, v5, vcc
	s_mov_b64 s[0:1], s[80:81]
	global_load_dwordx2 v[4:5], v[106:107], off offset:16
	global_load_dwordx2 v[72:73], v[106:107], off offset:32
	global_load_dwordx2 v[70:71], v[106:107], off offset:48
	global_load_dwordx2 v[68:69], v[106:107], off offset:64
	s_nop 0
	global_load_dwordx2 v[6:7], v[6:7], off
	s_nop 0
	global_load_dwordx2 v[112:113], v[106:107], off offset:80
	global_load_dwordx2 v[78:79], v[106:107], off offset:96
	global_load_dwordx2 v[76:77], v[106:107], off offset:112
	s_load_dwordx2 s[0:1], s[0:1], 0x68
	v_lshlrev_b32_e32 v156, 2, v132
	v_or_b32_e32 v157, s26, v85
	s_waitcnt lgkmcnt(0)
	global_load_dword v128, v156, s[0:1]
	s_mov_b64 s[0:1], s[80:81]
	s_load_dwordx2 s[28:29], s[0:1], 0x58
	s_waitcnt lgkmcnt(0)
	global_load_dwordx4 v[114:117], v139, s[28:29] offset:48
	global_load_dwordx4 v[118:121], v139, s[28:29] offset:32
	global_load_dwordx4 v[122:125], v139, s[28:29] offset:16
	global_load_dwordx4 v[134:137], v139, s[28:29]
	s_waitcnt vmcnt(24)
	v_and_b32_e32 v97, 0xffff0000, v8
	v_lshlrev_b32_e32 v82, 16, v8
	v_lshlrev_b32_e32 v130, 16, v10
	v_and_b32_e32 v131, 0xffff0000, v10
	v_mul_f32_e32 v10, v97, v97
	v_lshlrev_b32_e32 v101, 16, v9
	v_fmac_f32_e32 v10, v82, v82
	v_and_b32_e32 v129, 0xffff0000, v9
	v_fmac_f32_e32 v10, v101, v101
	v_fmac_f32_e32 v10, v129, v129
	v_fmac_f32_e32 v10, v130, v130
	v_lshlrev_b32_e32 v133, 16, v11
	v_fmac_f32_e32 v10, v131, v131
	v_and_b32_e32 v138, 0xffff0000, v11
	v_fmac_f32_e32 v10, v133, v133
	s_waitcnt vmcnt(23)
; __device__ __forceinline__ float bf_lo(unsigned w) { return __uint_as_float(w << 16); }
; __device__ __forceinline__ float bf_hi(unsigned w) { return __uint_as_float(w & 0xffff0000u); }
; __device__ __forceinline__ bf16 f2bf(float f) { return (bf16)(cvt_pk_nv(f, 0.f) & 0xffffu); }
;     __device__ __forceinline__ float* out() const { return (float*)karg_in(33); }
; __device__ __forceinline__ void gmlp_tile(const Ctx& C, int T, LAS unsigned char* lds, int wave, int lane, int tid) {
;     ...
;         __syncthreads();
;         {
;             float v[32]; float s = 0.f;
; #pragma unroll
;             for (int i = 0; i < 4; ++i) { const v4u w = vraw[i];
;                 v[8 * i + 0] = bf_lo(w.x); v[8 * i + 1] = bf_hi(w.x); v[8 * i + 2] = bf_lo(w.y); v[8 * i + 3] = bf_hi(w.y);
;                 v[8 * i + 4] = bf_lo(w.z); v[8 * i + 5] = bf_hi(w.z); v[8 * i + 6] = bf_lo(w.w); v[8 * i + 7] = bf_hi(w.w); }
;             if (h < 3) {
; #pragma unroll
;                 for (int i = 0; i < 4; ++i) vraw[i] = *(const v4u*)(vsrc + (h + 1) * 128 + 8 * i);
;             }
; #pragma unroll
;             for (int i = 0; i < 32; ++i) s += v[i] * v[i];
;             s += __shfl_xor(s, 1); s += __shfl_xor(s, 2);
;             const float r = rsqrtf(s * (1.f / 128.f) + EPS);
; #pragma unroll
;             for (int i = 0; i < 32; ++i) { v[i] = v[i] * r * gvv[i >> 2][i & 3]; VT[(q * 32 + i) * VT_STRIDE + row] = f2bf(v[i]); }
;             if (mode) { float* ov = C.out() + OFF_V_S + (size_t)row * AW + h * 128 + q * 32;
; #pragma unroll
;                 for (int i = 0; i < 8; ++i) *(v4f*)(ov + 4 * i) = (v4f){v[4 * i], v[4 * i + 1], v[4 * i + 2], v[4 * i + 3]}; }
;         }
;         __syncthreads();
	v_lshlrev_b32_e32 v140, 16, v12
	v_fmac_f32_e32 v10, v138, v138
	v_and_b32_e32 v141, 0xffff0000, v12
	v_fmac_f32_e32 v10, v140, v140
	v_lshlrev_b32_e32 v142, 16, v13
	v_fmac_f32_e32 v10, v141, v141
	v_and_b32_e32 v143, 0xffff0000, v13
	v_fmac_f32_e32 v10, v142, v142
	v_lshlrev_b32_e32 v144, 16, v14
	v_fmac_f32_e32 v10, v143, v143
	v_and_b32_e32 v145, 0xffff0000, v14
	v_fmac_f32_e32 v10, v144, v144
	v_lshlrev_b32_e32 v146, 16, v15
	v_fmac_f32_e32 v10, v145, v145
	v_and_b32_e32 v147, 0xffff0000, v15
	v_fmac_f32_e32 v10, v146, v146
	s_waitcnt vmcnt(22)
	v_lshlrev_b32_e32 v148, 16, v16
	v_fmac_f32_e32 v10, v147, v147
	v_and_b32_e32 v149, 0xffff0000, v16
	v_fmac_f32_e32 v10, v148, v148
	v_lshlrev_b32_e32 v150, 16, v17
	v_fmac_f32_e32 v10, v149, v149
	v_and_b32_e32 v151, 0xffff0000, v17
	v_fmac_f32_e32 v10, v150, v150
	v_lshlrev_b32_e32 v152, 16, v18
	v_fmac_f32_e32 v10, v151, v151
	v_and_b32_e32 v153, 0xffff0000, v18
	v_fmac_f32_e32 v10, v152, v152
	v_lshlrev_b32_e32 v154, 16, v19
	v_fmac_f32_e32 v10, v153, v153
	v_and_b32_e32 v155, 0xffff0000, v19
	v_fmac_f32_e32 v10, v154, v154
	s_waitcnt vmcnt(21)
	v_and_b32_e32 v74, 0xffff0000, v20
	v_lshlrev_b32_e32 v75, 16, v20
	v_fmac_f32_e32 v10, v155, v155
	v_pk_mul_f32 v[8:9], v[74:75], v[74:75]
	v_and_b32_e32 v102, 0xffff0000, v21
	v_add_f32_e32 v9, v9, v10
	v_lshlrev_b32_e32 v103, 16, v21
	v_add_f32_e32 v10, v8, v9
	v_pk_mul_f32 v[8:9], v[102:103], v[102:103]
	v_and_b32_e32 v110, 0xffff0000, v22
	v_add_f32_e32 v9, v9, v10
	v_lshlrev_b32_e32 v111, 16, v22
	v_add_f32_e32 v10, v8, v9
	v_pk_mul_f32 v[8:9], v[110:111], v[110:111]
	v_and_b32_e32 v126, 0xffff0000, v23
	v_add_f32_e32 v9, v9, v10
	v_lshlrev_b32_e32 v127, 16, v23
	v_add_f32_e32 v10, v8, v9
	v_pk_mul_f32 v[8:9], v[126:127], v[126:127]
	s_nop 0
	v_add_f32_e32 v9, v9, v10
	v_add_f32_e32 v16, v8, v9
	ds_bpermute_b32 v17, v183, v16
	global_load_dwordx4 v[8:11], v139, s[28:29] offset:112
	global_load_dwordx4 v[12:15], v139, s[28:29] offset:96
	s_waitcnt lgkmcnt(0)
	v_add_f32_e32 v24, v16, v17
	global_load_dwordx4 v[16:19], v139, s[28:29] offset:80
	global_load_dwordx4 v[20:23], v139, s[28:29] offset:64
	ds_bpermute_b32 v25, v184, v24
	s_waitcnt lgkmcnt(0)
	s_barrier
	v_add_f32_e32 v24, v24, v25
	v_fmamk_f32 v24, v24, 0x3c000000, v177
	v_mul_f32_e32 v25, 0x4b800000, v24
	v_cmp_gt_f32_e32 vcc, s38, v24
	s_nop 1
	v_cndmask_b32_e32 v24, v24, v25, vcc
	v_rsq_f32_e32 v158, v24
	global_load_dwordx4 v[24:27], v[108:109], off offset:304
	global_load_dwordx4 v[32:35], v[108:109], off offset:288
	global_load_dwordx4 v[40:43], v[108:109], off offset:272
	global_load_dwordx4 v[52:55], v[108:109], off offset:256
	v_mul_f32_e32 v159, 0x45800000, v158
	v_cndmask_b32_e32 v158, v158, v159, vcc
	v_mul_f32_e32 v82, v158, v82
	s_waitcnt vmcnt(8)
	v_mul_f32_e32 v82, v134, v82
	v_cvt_pk_bf16_f32 v82, v82, v83
	ds_write_b16 v174, v82
	v_mul_f32_e32 v82, v158, v97
	v_mul_f32_e32 v82, v135, v82
	v_cvt_pk_bf16_f32 v82, v82, v83
	ds_write_b16 v174, v82 offset:272
	v_mul_f32_e32 v82, v158, v101
	v_mul_f32_e32 v82, v136, v82
	v_cvt_pk_bf16_f32 v82, v82, v83
	ds_write_b16 v174, v82 offset:544
	v_mul_f32_e32 v82, v158, v129
	v_mul_f32_e32 v82, v137, v82
	v_cvt_pk_bf16_f32 v82, v82, v83
	ds_write_b16 v174, v82 offset:816
	v_mul_f32_e32 v82, v158, v130
	v_mul_f32_e32 v82, v122, v82
	v_cvt_pk_bf16_f32 v82, v82, v83
	ds_write_b16 v174, v82 offset:1088
	v_mul_f32_e32 v82, v158, v131
	v_mul_f32_e32 v82, v123, v82
	v_cvt_pk_bf16_f32 v82, v82, v83
	ds_write_b16 v174, v82 offset:1360
	v_mul_f32_e32 v82, v158, v133
	v_mul_f32_e32 v82, v124, v82
	v_cvt_pk_bf16_f32 v82, v82, v83
	ds_write_b16 v174, v82 offset:1632
	v_mul_f32_e32 v82, v158, v138
	v_mul_f32_e32 v82, v125, v82
	v_cvt_pk_bf16_f32 v82, v82, v83
	ds_write_b16 v174, v82 offset:1904
	v_mul_f32_e32 v82, v158, v140
	v_mul_f32_e32 v82, v118, v82
	v_cvt_pk_bf16_f32 v82, v82, v83
	ds_write_b16 v174, v82 offset:2176
	v_mul_f32_e32 v82, v158, v141
	v_mul_f32_e32 v82, v119, v82
	v_cvt_pk_bf16_f32 v82, v82, v83
	ds_write_b16 v174, v82 offset:2448
	v_mul_f32_e32 v82, v158, v142
	v_mul_f32_e32 v82, v120, v82
	v_cvt_pk_bf16_f32 v82, v82, v83
	ds_write_b16 v174, v82 offset:2720
	v_mul_f32_e32 v82, v158, v143
	v_mul_f32_e32 v82, v121, v82
	v_cvt_pk_bf16_f32 v82, v82, v83
	ds_write_b16 v174, v82 offset:2992
	v_mul_f32_e32 v82, v158, v144
	v_mul_f32_e32 v82, v114, v82
	v_cvt_pk_bf16_f32 v82, v82, v83
	ds_write_b16 v174, v82 offset:3264
	v_mul_f32_e32 v82, v158, v145
	v_mul_f32_e32 v82, v115, v82
	v_cvt_pk_bf16_f32 v82, v82, v83
	ds_write_b16 v174, v82 offset:3536
	v_mul_f32_e32 v82, v158, v146
	v_mul_f32_e32 v82, v116, v82
	v_cvt_pk_bf16_f32 v82, v82, v83
	ds_write_b16 v174, v82 offset:3808
	v_mul_f32_e32 v82, v158, v147
	v_mul_f32_e32 v82, v117, v82
	v_cvt_pk_bf16_f32 v82, v82, v83
	ds_write_b16 v174, v82 offset:4080
	v_mul_f32_e32 v82, v158, v148
	s_waitcnt vmcnt(4)
	v_mul_f32_e32 v20, v20, v82
	v_cvt_pk_bf16_f32 v20, v20, v83
	ds_write_b16 v174, v20 offset:4352
	v_mul_f32_e32 v20, v158, v149
	v_mul_f32_e32 v20, v21, v20
	v_cvt_pk_bf16_f32 v20, v20, v83
	ds_write_b16 v174, v20 offset:4624
	v_mul_f32_e32 v20, v158, v150
	v_mul_f32_e32 v20, v22, v20
	v_cvt_pk_bf16_f32 v20, v20, v83
	ds_write_b16 v174, v20 offset:4896
	v_mul_f32_e32 v20, v158, v151
	v_mul_f32_e32 v20, v23, v20
	v_cvt_pk_bf16_f32 v20, v20, v83
	ds_write_b16 v174, v20 offset:5168
	v_mul_f32_e32 v20, v158, v152
	v_mul_f32_e32 v16, v16, v20
	v_cvt_pk_bf16_f32 v16, v16, v83
	ds_write_b16 v174, v16 offset:5440
	v_mul_f32_e32 v16, v158, v153
	v_mul_f32_e32 v16, v17, v16
	v_cvt_pk_bf16_f32 v16, v16, v83
	ds_write_b16 v174, v16 offset:5712
	v_mul_f32_e32 v16, v158, v154
	v_mul_f32_e32 v16, v18, v16
	v_cvt_pk_bf16_f32 v16, v16, v83
	ds_write_b16 v174, v16 offset:5984
	v_mul_f32_e32 v16, v158, v155
	v_mul_f32_e32 v16, v19, v16
	v_cvt_pk_bf16_f32 v16, v16, v83
	ds_write_b16 v174, v16 offset:6256
	v_mul_f32_e32 v16, v158, v75
	v_mul_f32_e32 v12, v12, v16
	v_cvt_pk_bf16_f32 v12, v12, v83
	ds_write_b16 v174, v12 offset:6528
	v_mul_f32_e32 v12, v158, v74
	v_mul_f32_e32 v12, v13, v12
	v_cvt_pk_bf16_f32 v12, v12, v83
	ds_write_b16 v174, v12 offset:6800
	v_mul_f32_e32 v12, v158, v103
	v_mul_f32_e32 v12, v14, v12
	v_cvt_pk_bf16_f32 v12, v12, v83
	ds_write_b16 v174, v12 offset:7072
	v_mul_f32_e32 v12, v158, v102
	v_mul_f32_e32 v12, v15, v12
	v_cvt_pk_bf16_f32 v12, v12, v83
	ds_write_b16 v174, v12 offset:7344
	v_mul_f32_e32 v12, v158, v111
	v_mul_f32_e32 v8, v8, v12
	v_cvt_pk_bf16_f32 v8, v8, v83
	ds_write_b16 v174, v8 offset:7616
	v_mul_f32_e32 v8, v158, v110
	v_mul_f32_e32 v8, v9, v8
	v_cvt_pk_bf16_f32 v8, v8, v83
	ds_write_b16 v174, v8 offset:7888
	v_mul_f32_e32 v8, v158, v127
	v_mul_f32_e32 v8, v10, v8
	v_cvt_pk_bf16_f32 v8, v8, v83
	ds_write_b16 v174, v8 offset:8160
	v_mul_f32_e32 v8, v158, v126
	v_mul_f32_e32 v8, v11, v8
	v_cvt_pk_bf16_f32 v8, v8, v83
	v_mad_u64_u32 v[102:103], s[0:1], v157, s30, v[90:91]
	ds_write_b16 v174, v8 offset:8432
	s_waitcnt lgkmcnt(0)
	s_barrier
; __device__ __forceinline__ float bf_lo(unsigned w) { return __uint_as_float(w << 16); }
; __device__ __forceinline__ float bf_hi(unsigned w) { return __uint_as_float(w & 0xffff0000u); }
; #define LAS __attribute__((address_space(3)))
; __device__ __forceinline__ unsigned cvt_pk_nv(float lo, float hi) { unsigned r; asm("v_cvt_pk_bf16_f32 %0, %1, %2" : "=v"(r) : "v"(lo), "v"(hi)); return r; }
; __device__ __forceinline__ void gmlp_tile(const Ctx& C, int T, LAS unsigned char* lds, int wave, int lane, int tid) {
;     ...
; #pragma unroll
;         for (int dbi = 0; dbi < 2; ++dbi) {
;             const int db = 2 * dh + dbi;
;             v16f acc;
; #pragma unroll
;             for (int r = 0; r < 16; ++r) acc[r] = 0.f;
; #pragma unroll
;             for (int ks = 0; ks < 8; ++ks) {
;                 const bfx8 va = *(const LAS bfx8*)(VT + (32 * db + tl) * VT_STRIDE + 16 * ks + 8 * hh);
;                 acc = __builtin_amdgcn_mfma_f32_32x32x16_bf16(va, wf[ks], acc, 0, 0, 0);
;             }
; #pragma unroll
;             for (int rg = 0; rg < 4; ++rg) {
;                 const v2u u2 = uw[dbi][rg];
;                 const float o0 = bf_lo(u2.x) * (acc[4 * rg + 0] + bias), o1 = bf_hi(u2.x) * (acc[4 * rg + 1] + bias);
;                 const float o2 = bf_lo(u2.y) * (acc[4 * rg + 2] + bias), o3 = bf_hi(u2.y) * (acc[4 * rg + 3] + bias);
;                 ssq += (o0 * o0 + o1 * o1) + (o2 * o2 + o3 * o3);
;                 outp[h][dbi][2 * rg] = cvt_pk_nv(o0, o1); outp[h][dbi][2 * rg + 1] = cvt_pk_nv(o2, o3);
;             }
;         }
	ds_read_b128 v[8:11], v102
	ds_read_b128 v[114:117], v102 offset:32
	s_waitcnt lgkmcnt(1)
	v_mfma_f32_32x32x16_bf16 v[8:23], v[8:11], v[0:3], 0
	v_lshlrev_b32_e32 v74, 16, v6
	v_and_b32_e32 v6, 0xffff0000, v6
	s_mov_b64 s[0:1], s[80:81]
	s_waitcnt vmcnt(0)
	v_and_b32_e32 v164, 0xffff0000, v52
	v_lshlrev_b32_e32 v158, 16, v52
	v_lshlrev_b32_e32 v200, 16, v34
	v_and_b32_e32 v201, 0xffff0000, v34
	s_waitcnt lgkmcnt(0)
	v_mfma_f32_32x32x16_bf16 v[8:23], v[114:117], v[64:67], v[8:23]
	ds_read_b128 v[114:117], v102 offset:64
	ds_read_b128 v[118:121], v102 offset:96
	v_mul_f32_e32 v34, v164, v164
	v_lshlrev_b32_e32 v165, 16, v53
	v_fmac_f32_e32 v34, v158, v158
	v_and_b32_e32 v166, 0xffff0000, v53
	v_fmac_f32_e32 v34, v165, v165
	v_lshlrev_b32_e32 v167, 16, v54
	s_waitcnt lgkmcnt(1)
	v_mfma_f32_32x32x16_bf16 v[8:23], v[114:117], v[60:63], v[8:23]
	v_fmac_f32_e32 v34, v166, v166
	v_and_b32_e32 v178, 0xffff0000, v54
	v_fmac_f32_e32 v34, v167, v167
	v_lshlrev_b32_e32 v179, 16, v55
	v_fmac_f32_e32 v34, v178, v178
	v_and_b32_e32 v180, 0xffff0000, v55
	v_fmac_f32_e32 v34, v179, v179
	s_waitcnt lgkmcnt(0)
	v_mfma_f32_32x32x16_bf16 v[8:23], v[118:121], v[56:59], v[8:23]
	ds_read_b128 v[114:117], v102 offset:128
	ds_read_b128 v[118:121], v102 offset:160
	v_lshlrev_b32_e32 v181, 16, v40
	v_fmac_f32_e32 v34, v180, v180
	v_and_b32_e32 v189, 0xffff0000, v40
	v_fmac_f32_e32 v34, v181, v181
	v_lshlrev_b32_e32 v190, 16, v41
	v_fmac_f32_e32 v34, v189, v189
	s_waitcnt lgkmcnt(1)
	v_mfma_f32_32x32x16_bf16 v[8:23], v[114:117], v[48:51], v[8:23]
	v_and_b32_e32 v191, 0xffff0000, v41
	v_fmac_f32_e32 v34, v190, v190
	v_lshlrev_b32_e32 v192, 16, v42
	v_fmac_f32_e32 v34, v191, v191
	v_and_b32_e32 v193, 0xffff0000, v42
	v_fmac_f32_e32 v34, v192, v192
	v_lshlrev_b32_e32 v194, 16, v43
	s_waitcnt lgkmcnt(0)
	v_mfma_f32_32x32x16_bf16 v[8:23], v[118:121], v[44:47], v[8:23]
	ds_read_b128 v[114:117], v102 offset:192
	ds_read_b128 v[118:121], v102 offset:224
	v_fmac_f32_e32 v34, v193, v193
	v_and_b32_e32 v195, 0xffff0000, v43
	v_fmac_f32_e32 v34, v194, v194
	v_lshlrev_b32_e32 v196, 16, v32
	v_fmac_f32_e32 v34, v195, v195
	v_and_b32_e32 v197, 0xffff0000, v32
	s_waitcnt lgkmcnt(1)
	v_mfma_f32_32x32x16_bf16 v[8:23], v[114:117], v[36:39], v[8:23]
	ds_read_b128 v[114:117], v102 offset:8736
	v_fmac_f32_e32 v34, v196, v196
	v_lshlrev_b32_e32 v198, 16, v33
	v_fmac_f32_e32 v34, v197, v197
	v_and_b32_e32 v199, 0xffff0000, v33
	v_fmac_f32_e32 v34, v198, v198
	v_fmac_f32_e32 v34, v199, v199
	s_waitcnt lgkmcnt(1)
	v_mfma_f32_32x32x16_bf16 v[8:23], v[118:121], v[28:31], v[8:23]
	ds_read_b128 v[118:121], v102 offset:8768
	v_fmac_f32_e32 v34, v200, v200
	v_lshlrev_b32_e32 v202, 16, v35
	v_fmac_f32_e32 v34, v201, v201
	v_and_b32_e32 v203, 0xffff0000, v35
	v_fmac_f32_e32 v34, v202, v202
	v_fmac_f32_e32 v34, v203, v203
	s_nop 4
	v_add_f32_e32 v9, v128, v9
	v_mul_f32_e32 v6, v9, v6
	v_lshlrev_b32_e32 v9, 16, v7
	v_add_f32_e32 v10, v128, v10
	v_mul_f32_e32 v9, v10, v9
	v_and_b32_e32 v7, 0xffff0000, v7
	v_add_f32_e32 v10, v128, v11
	v_add_f32_e32 v8, v128, v8
	v_mul_f32_e32 v7, v10, v7
	v_mul_f32_e32 v8, v8, v74
	v_mul_f32_e32 v10, v6, v6
	v_mul_f32_e32 v11, v7, v7
	v_cvt_pk_bf16_f32 v97, v8, v6
	v_cvt_pk_bf16_f32 v82, v9, v7
	v_lshlrev_b32_e32 v6, 16, v4
	v_add_f32_e32 v7, v128, v12
	v_mul_f32_e32 v75, v7, v6
	v_and_b32_e32 v4, 0xffff0000, v4
	v_add_f32_e32 v6, v128, v13
	v_mul_f32_e32 v101, v6, v4
	v_lshlrev_b32_e32 v4, 16, v5
	v_add_f32_e32 v6, v128, v14
	v_fmac_f32_e32 v10, v8, v8
	v_mul_f32_e32 v103, v6, v4
	v_and_b32_e32 v8, 0xffff0000, v5
	ds_read_b128 v[4:7], v102 offset:8704
	v_fmac_f32_e32 v11, v9, v9
	v_add_f32_e32 v9, v128, v15
	v_mul_f32_e32 v110, v9, v8
	v_mul_f32_e32 v8, v101, v101
	v_mul_f32_e32 v9, v110, v110
	v_fmac_f32_e32 v8, v75, v75
	v_fmac_f32_e32 v9, v103, v103
	v_add_f32_e32 v74, v10, v11
	v_add_f32_e32 v111, v8, v9
	s_waitcnt lgkmcnt(0)
	v_mfma_f32_32x32x16_bf16 v[0:15], v[4:7], v[0:3], 0
	v_cvt_pk_bf16_f32 v134, v75, v101
	v_lshlrev_b32_e32 v75, 16, v72
	v_add_f32_e32 v16, v128, v16
	v_mul_f32_e32 v75, v16, v75
	v_and_b32_e32 v16, 0xffff0000, v72
	v_add_f32_e32 v17, v128, v17
	v_mul_f32_e32 v72, v17, v16
	v_mfma_f32_32x32x16_bf16 v[0:15], v[114:117], v[64:67], v[0:15]
	ds_read_b128 v[64:67], v102 offset:8800
	v_lshlrev_b32_e32 v16, 16, v73
	v_add_f32_e32 v17, v128, v18
	v_mul_f32_e32 v101, v17, v16
	v_and_b32_e32 v16, 0xffff0000, v73
	v_add_f32_e32 v17, v128, v19
	v_add_f32_e32 v74, v74, v111
	v_mfma_f32_32x32x16_bf16 v[0:15], v[118:121], v[60:63], v[0:15]
	v_mul_f32_e32 v60, v17, v16
	ds_read_b128 v[16:19], v102 offset:8832
	v_mul_f32_e32 v61, v72, v72
	v_mul_f32_e32 v62, v60, v60
	v_fmac_f32_e32 v61, v75, v75
	v_fmac_f32_e32 v62, v101, v101
	v_cvt_pk_bf16_f32 v135, v101, v60
	s_waitcnt lgkmcnt(1)
	v_mfma_f32_32x32x16_bf16 v[0:15], v[64:67], v[56:59], v[0:15]
	v_add_f32_e32 v56, v61, v62
	v_add_f32_e32 v61, v56, v74
	ds_read_b128 v[56:59], v102 offset:8864
	v_lshlrev_b32_e32 v60, 16, v70
	v_cvt_pk_bf16_f32 v133, v103, v110
	v_cvt_pk_bf16_f32 v136, v75, v72
	v_and_b32_e32 v130, 0xffff0000, v25
	s_waitcnt lgkmcnt(1)
	v_mfma_f32_32x32x16_bf16 v[0:15], v[16:19], v[48:51], v[0:15]
	v_add_f32_e32 v16, v128, v20
	v_mul_f32_e32 v48, v16, v60
	v_and_b32_e32 v16, 0xffff0000, v70
	v_add_f32_e32 v17, v128, v21
	v_mul_f32_e32 v49, v17, v16
	ds_read_b128 v[16:19], v102 offset:8896
	v_lshlrev_b32_e32 v20, 16, v71
	s_waitcnt lgkmcnt(1)
	v_mfma_f32_32x32x16_bf16 v[0:15], v[56:59], v[44:47], v[0:15]
	v_add_f32_e32 v21, v128, v22
	v_mul_f32_e32 v44, v21, v20
	v_and_b32_e32 v20, 0xffff0000, v71
	v_add_f32_e32 v21, v128, v23
	v_mul_f32_e32 v45, v21, v20
	ds_read_b128 v[20:23], v102 offset:8928
	v_mul_f32_e32 v46, v49, v49
	s_waitcnt lgkmcnt(1)
; __device__ __forceinline__ float bf_lo(unsigned w) { return __uint_as_float(w << 16); }
; __device__ __forceinline__ void gmlp_tile(const Ctx& C, int T, LAS unsigned char* lds, int wave, int lane, int tid) {
;     ...
;         bfx8 wf[8];
;         const bf16* wrow = Weff + ((size_t)(mode * 4 + h) * 128 + t) * 128 + 8 * hh;
; #pragma unroll
;         for (int ks = 0; ks < 8; ++ks) wf[ks] = *(const bfx8*)(wrow + 16 * ks);
;         v2u uw[2][4];
; #pragma unroll
;         for (int dbi = 0; dbi < 2; ++dbi)
; #pragma unroll
;             for (int rg = 0; rg < 4; ++rg) uw[dbi][rg] = *(const v2u*)(zt + h * 128 + 32 * (2 * dh + dbi) + 8 * rg + 4 * hh);
;         const float bias = C.in(13)[h * 128 + (mode ? (t & 15) : t)];
;         v4f gvv[8];
;         { const float* gvp = C.in(11) + h * 128 + q * 32;
; #pragma unroll
;           for (int i = 0; i < 8; ++i) gvv[i] = *(const v4f*)(gvp + 4 * i); }
;         __syncthreads();
;         {
;             float v[32]; float s = 0.f;
; #pragma unroll
;             for (int i = 0; i < 4; ++i) { const v4u w = vraw[i];
;                 v[8 * i + 0] = bf_lo(w.x); v[8 * i + 1] = bf_hi(w.x); v[8 * i + 2] = bf_lo(w.y); v[8 * i + 3] = bf_hi(w.y);
;                 v[8 * i + 4] = bf_lo(w.z); v[8 * i + 5] = bf_hi(w.z); v[8 * i + 6] = bf_lo(w.w); v[8 * i + 7] = bf_hi(w.w); }
;             if (h < 3) {
; #pragma unroll
;                 for (int i = 0; i < 4; ++i) vraw[i] = *(const v4u*)(vsrc + (h + 1) * 128 + 8 * i);
;             }
; #pragma unroll
;             for (int i = 0; i < 32; ++i) s += v[i] * v[i];
;             s += __shfl_xor(s, 1); s += __shfl_xor(s, 2);
;             const float r = rsqrtf(s * (1.f / 128.f) + EPS);
; #pragma unroll
;             for (int i = 0; i < 32; ++i) { v[i] = v[i] * r * gvv[i >> 2][i & 3]; VT[(q * 32 + i) * VT_STRIDE + row] = f2bf(v[i]); }
;     ...
;             for (int rg = 0; rg < 4; ++rg) {
;                 const v2u u2 = uw[dbi][rg];
;                 const float o0 = bf_lo(u2.x) * (acc[4 * rg + 0] + bias), o1 = bf_hi(u2.x) * (acc[4 * rg + 1] + bias);
;                 const float o2 = bf_lo(u2.y) * (acc[4 * rg + 2] + bias), o3 = bf_hi(u2.y) * (acc[4 * rg + 3] + bias);
;                 ssq += (o0 * o0 + o1 * o1) + (o2 * o2 + o3 * o3);
;                 outp[h][dbi][2 * rg] = cvt_pk_nv(o0, o1); outp[h][dbi][2 * rg + 1] = cvt_pk_nv(o2, o3);
;             }
	v_mfma_f32_32x32x16_bf16 v[0:15], v[16:19], v[36:39], v[0:15]
	v_lshlrev_b32_e32 v17, 16, v68
	v_mul_f32_e32 v16, v45, v45
	v_fmac_f32_e32 v46, v48, v48
	v_fmac_f32_e32 v16, v44, v44
	v_add_f32_e32 v16, v46, v16
	v_add_f32_e32 v16, v16, v61
	v_cvt_pk_bf16_f32 v138, v48, v49
	s_waitcnt lgkmcnt(0)
	v_mfma_f32_32x32x16_bf16 v[0:15], v[20:23], v[28:31], v[0:15]
	v_cvt_pk_bf16_f32 v137, v44, v45
	v_lshlrev_b32_e32 v131, 16, v25
	v_and_b32_e32 v160, 0xffff0000, v26
	v_lshlrev_b32_e32 v161, 16, v26
	v_and_b32_e32 v162, 0xffff0000, v27
	v_lshlrev_b32_e32 v163, 16, v27
	v_lshlrev_b32_e32 v60, 16, v113
	s_nop 5
	v_add_f32_e32 v0, v128, v0
	v_mul_f32_e32 v0, v0, v17
	v_and_b32_e32 v17, 0xffff0000, v68
	v_add_f32_e32 v1, v128, v1
	v_mul_f32_e32 v1, v1, v17
	v_lshlrev_b32_e32 v17, 16, v69
	v_add_f32_e32 v2, v128, v2
	v_mul_f32_e32 v2, v2, v17
	v_and_b32_e32 v17, 0xffff0000, v69
	v_add_f32_e32 v3, v128, v3
	v_mul_f32_e32 v3, v3, v17
	v_mul_f32_e32 v17, v1, v1
	v_mul_f32_e32 v18, v3, v3
	v_fmac_f32_e32 v17, v0, v0
	v_fmac_f32_e32 v18, v2, v2
	v_add_f32_e32 v17, v17, v18
	v_add_f32_e32 v129, v16, v17
	v_add_co_u32_e32 v16, vcc, s39, v104
	v_cvt_pk_bf16_f32 v103, v0, v1
	v_cvt_pk_bf16_f32 v101, v2, v3
	v_add_f32_e32 v4, v128, v4
	s_nop 0
	v_addc_co_u32_e32 v17, vcc, 0, v105, vcc
	global_load_dwordx4 v[0:3], v[16:17], off offset:-3584
	global_load_dwordx4 v[72:75], v[16:17], off offset:-2560
	global_load_dwordx4 v[68:71], v[16:17], off offset:-1536
	global_load_dwordx4 v[64:67], v[16:17], off offset:-512
	global_load_dwordx4 v[56:59], v[16:17], off offset:512
	global_load_dwordx4 v[48:51], v[16:17], off offset:1536
	global_load_dwordx4 v[44:47], v[16:17], off offset:2560
	global_load_dwordx4 v[36:39], v[16:17], off offset:3584
	global_load_dwordx2 v[126:127], v[106:107], off offset:256
	global_load_dwordx2 v[124:125], v[106:107], off offset:272
	global_load_dwordx2 v[122:123], v[106:107], off offset:288
	global_load_dwordx2 v[118:119], v[106:107], off offset:304
	global_load_dwordx2 v[116:117], v[106:107], off offset:320
	global_load_dwordx2 v[120:121], v[106:107], off offset:336
	global_load_dwordx2 v[114:115], v[106:107], off offset:352
	global_load_dwordx2 v[110:111], v[106:107], off offset:368
	s_load_dwordx2 s[0:1], s[0:1], 0x68
	v_lshlrev_b32_e32 v16, 16, v112
	v_mul_f32_e32 v157, v4, v16
	v_and_b32_e32 v4, 0xffff0000, v112
	v_add_f32_e32 v5, v128, v5
	s_waitcnt lgkmcnt(0)
	global_load_dword v159, v156, s[0:1] offset:512
	s_mov_b64 s[0:1], s[80:81]
	s_load_dwordx2 s[28:29], s[0:1], 0x58
	s_waitcnt lgkmcnt(0)
	global_load_dwordx4 v[16:19], v139, s[28:29] offset:560
	global_load_dwordx4 v[20:23], v139, s[28:29] offset:544
	global_load_dwordx4 v[28:31], v139, s[28:29] offset:528
	global_load_dwordx4 v[140:143], v139, s[28:29] offset:512
	v_mul_f32_e32 v112, v5, v4
	v_and_b32_e32 v4, 0xffff0000, v24
	v_lshlrev_b32_e32 v5, 16, v24
	v_pk_mul_f32 v[32:33], v[4:5], v[4:5]
	v_add_f32_e32 v6, v128, v6
	v_add_f32_e32 v24, v33, v34
	v_add_f32_e32 v32, v32, v24
	v_pk_mul_f32 v[24:25], v[130:131], v[130:131]
	v_mul_f32_e32 v204, v6, v60
	v_add_f32_e32 v25, v25, v32
	v_add_f32_e32 v32, v24, v25
	v_pk_mul_f32 v[24:25], v[160:161], v[160:161]
	v_and_b32_e32 v6, 0xffff0000, v113
	v_add_f32_e32 v25, v25, v32
	v_add_f32_e32 v26, v24, v25
	v_pk_mul_f32 v[24:25], v[162:163], v[162:163]
	v_add_f32_e32 v8, v128, v8
	v_add_f32_e32 v25, v25, v26
	v_add_f32_e32 v32, v24, v25
	global_load_dwordx4 v[24:27], v139, s[28:29] offset:624
	global_load_dwordx4 v[144:147], v139, s[28:29] offset:608
	global_load_dwordx4 v[148:151], v139, s[28:29] offset:592
	global_load_dwordx4 v[152:155], v139, s[28:29] offset:576
	ds_bpermute_b32 v33, v183, v32
	s_waitcnt lgkmcnt(0)
	s_barrier
	s_mov_b64 s[0:1], s[80:81]
	v_add_f32_e32 v32, v32, v33
	ds_bpermute_b32 v33, v184, v32
	s_waitcnt lgkmcnt(0)
	v_add_f32_e32 v32, v32, v33
	v_fmamk_f32 v32, v32, 0x3c000000, v177
	v_mul_f32_e32 v33, 0x4b800000, v32
	v_cmp_gt_f32_e32 vcc, s38, v32
	s_nop 1
	v_cndmask_b32_e32 v32, v32, v33, vcc
	v_rsq_f32_e32 v113, v32
	global_load_dwordx4 v[32:35], v[108:109], off offset:560
	global_load_dwordx4 v[40:43], v[108:109], off offset:544
	global_load_dwordx4 v[52:55], v[108:109], off offset:528
	global_load_dwordx4 v[60:63], v[108:109], off offset:512
	v_mul_f32_e32 v205, 0x45800000, v113
	v_cndmask_b32_e32 v113, v113, v205, vcc
	v_mul_f32_e32 v158, v113, v158
	v_mul_f32_e32 v4, v113, v4
	v_mul_f32_e32 v5, v113, v5
	s_waitcnt vmcnt(8)
	v_mul_f32_e32 v140, v140, v158
	v_cvt_pk_bf16_f32 v140, v140, v83
	ds_write_b16 v174, v140
	v_mul_f32_e32 v140, v113, v164
	v_mul_f32_e32 v140, v141, v140
	v_cvt_pk_bf16_f32 v140, v140, v83
	ds_write_b16 v174, v140 offset:272
	v_mul_f32_e32 v140, v113, v165
	v_mul_f32_e32 v140, v142, v140
	v_cvt_pk_bf16_f32 v140, v140, v83
	ds_write_b16 v174, v140 offset:544
	v_mul_f32_e32 v140, v113, v166
	v_mul_f32_e32 v140, v143, v140
	v_cvt_pk_bf16_f32 v140, v140, v83
	ds_write_b16 v174, v140 offset:816
	v_mul_f32_e32 v140, v113, v167
	v_mul_f32_e32 v28, v28, v140
	v_cvt_pk_bf16_f32 v28, v28, v83
	ds_write_b16 v174, v28 offset:1088
	v_mul_f32_e32 v28, v113, v178
	v_mul_f32_e32 v28, v29, v28
	v_cvt_pk_bf16_f32 v28, v28, v83
	ds_write_b16 v174, v28 offset:1360
	v_mul_f32_e32 v28, v113, v179
	v_mul_f32_e32 v28, v30, v28
	v_cvt_pk_bf16_f32 v28, v28, v83
	ds_write_b16 v174, v28 offset:1632
	v_mul_f32_e32 v28, v113, v180
	v_mul_f32_e32 v28, v31, v28
	v_cvt_pk_bf16_f32 v28, v28, v83
	ds_write_b16 v174, v28 offset:1904
	v_mul_f32_e32 v28, v113, v181
	v_mul_f32_e32 v20, v20, v28
	v_cvt_pk_bf16_f32 v20, v20, v83
	ds_write_b16 v174, v20 offset:2176
	v_mul_f32_e32 v20, v113, v189
	v_mul_f32_e32 v20, v21, v20
	v_cvt_pk_bf16_f32 v20, v20, v83
	ds_write_b16 v174, v20 offset:2448
	v_mul_f32_e32 v20, v113, v190
	v_mul_f32_e32 v20, v22, v20
	v_cvt_pk_bf16_f32 v20, v20, v83
	ds_write_b16 v174, v20 offset:2720
	v_mul_f32_e32 v20, v113, v191
	v_mul_f32_e32 v20, v23, v20
	v_cvt_pk_bf16_f32 v20, v20, v83
	ds_write_b16 v174, v20 offset:2992
	v_mul_f32_e32 v20, v113, v192
	v_mul_f32_e32 v16, v16, v20
	v_cvt_pk_bf16_f32 v16, v16, v83
	ds_write_b16 v174, v16 offset:3264
	v_mul_f32_e32 v16, v113, v193
	v_mul_f32_e32 v16, v17, v16
	v_cvt_pk_bf16_f32 v16, v16, v83
	ds_write_b16 v174, v16 offset:3536
	v_mul_f32_e32 v16, v113, v194
	v_mul_f32_e32 v16, v18, v16
	v_cvt_pk_bf16_f32 v16, v16, v83
	ds_write_b16 v174, v16 offset:3808
	v_mul_f32_e32 v16, v113, v195
	v_mul_f32_e32 v16, v19, v16
	v_cvt_pk_bf16_f32 v16, v16, v83
	ds_write_b16 v174, v16 offset:4080
	v_mul_f32_e32 v16, v113, v196
	s_waitcnt vmcnt(4)
; __device__ __forceinline__ float bf_lo(unsigned w) { return __uint_as_float(w << 16); }
; __device__ __forceinline__ float bf_hi(unsigned w) { return __uint_as_float(w & 0xffff0000u); }
; #define LAS __attribute__((address_space(3)))
; __device__ __forceinline__ unsigned cvt_pk_nv(float lo, float hi) { unsigned r; asm("v_cvt_pk_bf16_f32 %0, %1, %2" : "=v"(r) : "v"(lo), "v"(hi)); return r; }
; __device__ __forceinline__ bf16 f2bf(float f) { return (bf16)(cvt_pk_nv(f, 0.f) & 0xffffu); }
;     __device__ __forceinline__ float* out() const { return (float*)karg_in(33); }
; __device__ __forceinline__ void gmlp_tile(const Ctx& C, int T, LAS unsigned char* lds, int wave, int lane, int tid) {
;     ...
;             for (int i = 0; i < 32; ++i) { v[i] = v[i] * r * gvv[i >> 2][i & 3]; VT[(q * 32 + i) * VT_STRIDE + row] = f2bf(v[i]); }
;             if (mode) { float* ov = C.out() + OFF_V_S + (size_t)row * AW + h * 128 + q * 32;
; #pragma unroll
;                 for (int i = 0; i < 8; ++i) *(v4f*)(ov + 4 * i) = (v4f){v[4 * i], v[4 * i + 1], v[4 * i + 2], v[4 * i + 3]}; }
;         }
;         __syncthreads();
; #pragma unroll
;         for (int dbi = 0; dbi < 2; ++dbi) {
;             const int db = 2 * dh + dbi;
;             v16f acc;
; #pragma unroll
;             for (int r = 0; r < 16; ++r) acc[r] = 0.f;
; #pragma unroll
;             for (int ks = 0; ks < 8; ++ks) {
;                 const bfx8 va = *(const LAS bfx8*)(VT + (32 * db + tl) * VT_STRIDE + 16 * ks + 8 * hh);
;                 acc = __builtin_amdgcn_mfma_f32_32x32x16_bf16(va, wf[ks], acc, 0, 0, 0);
;             }
; #pragma unroll
;             for (int rg = 0; rg < 4; ++rg) {
;                 const v2u u2 = uw[dbi][rg];
;                 const float o0 = bf_lo(u2.x) * (acc[4 * rg + 0] + bias), o1 = bf_hi(u2.x) * (acc[4 * rg + 1] + bias);
;                 const float o2 = bf_lo(u2.y) * (acc[4 * rg + 2] + bias), o3 = bf_hi(u2.y) * (acc[4 * rg + 3] + bias);
;                 ssq += (o0 * o0 + o1 * o1) + (o2 * o2 + o3 * o3);
;                 outp[h][dbi][2 * rg] = cvt_pk_nv(o0, o1); outp[h][dbi][2 * rg + 1] = cvt_pk_nv(o2, o3);
;             }
	v_mul_f32_e32 v16, v152, v16
	v_cvt_pk_bf16_f32 v16, v16, v83
	ds_write_b16 v174, v16 offset:4352
	v_mul_f32_e32 v16, v113, v197
	v_mul_f32_e32 v16, v153, v16
	v_cvt_pk_bf16_f32 v16, v16, v83
	v_mul_f32_e32 v4, v145, v4
	ds_write_b16 v174, v16 offset:4624
	v_mul_f32_e32 v16, v113, v198
	v_cvt_pk_bf16_f32 v4, v4, v83
	v_mul_f32_e32 v16, v154, v16
	ds_write_b16 v174, v4 offset:6800
	v_mul_f32_e32 v4, v113, v131
	v_cvt_pk_bf16_f32 v16, v16, v83
	v_mul_f32_e32 v4, v146, v4
	ds_write_b16 v174, v16 offset:4896
	v_mul_f32_e32 v16, v113, v199
	v_cvt_pk_bf16_f32 v4, v4, v83
	v_mul_f32_e32 v16, v155, v16
	ds_write_b16 v174, v4 offset:7072
	v_mul_f32_e32 v4, v113, v130
	v_cvt_pk_bf16_f32 v16, v16, v83
	v_mul_f32_e32 v4, v147, v4
	ds_write_b16 v174, v16 offset:5168
	v_mul_f32_e32 v16, v113, v200
	v_cvt_pk_bf16_f32 v4, v4, v83
	v_mul_f32_e32 v16, v148, v16
	ds_write_b16 v174, v4 offset:7344
	v_mul_f32_e32 v4, v113, v161
	v_cvt_pk_bf16_f32 v16, v16, v83
	v_mul_f32_e32 v4, v24, v4
	ds_write_b16 v174, v16 offset:5440
	v_mul_f32_e32 v16, v113, v201
	v_cvt_pk_bf16_f32 v4, v4, v83
	v_mul_f32_e32 v16, v149, v16
	ds_write_b16 v174, v4 offset:7616
	v_mul_f32_e32 v4, v113, v160
	v_cvt_pk_bf16_f32 v16, v16, v83
	v_mul_f32_e32 v4, v25, v4
	ds_write_b16 v174, v16 offset:5712
	v_mul_f32_e32 v16, v113, v202
	v_cvt_pk_bf16_f32 v4, v4, v83
	v_mul_f32_e32 v16, v150, v16
	ds_write_b16 v174, v4 offset:7888
	v_mul_f32_e32 v4, v113, v163
	v_cvt_pk_bf16_f32 v16, v16, v83
	v_mul_f32_e32 v4, v26, v4
	ds_write_b16 v174, v16 offset:5984
	v_mul_f32_e32 v16, v113, v203
	v_cvt_pk_bf16_f32 v4, v4, v83
	v_mul_f32_e32 v16, v151, v16
	ds_write_b16 v174, v4 offset:8160
	v_mul_f32_e32 v4, v113, v162
	v_cvt_pk_bf16_f32 v16, v16, v83
	v_mul_f32_e32 v5, v144, v5
	v_mul_f32_e32 v4, v27, v4
	ds_write_b16 v174, v16 offset:6256
	v_cvt_pk_bf16_f32 v5, v5, v83
	ds_write_b16 v174, v5 offset:6528
	v_cvt_pk_bf16_f32 v4, v4, v83
	ds_write_b16 v174, v4 offset:8432
	s_waitcnt lgkmcnt(0)
	s_barrier
	ds_read_b128 v[16:19], v102
	v_add_f32_e32 v4, v128, v7
	v_mul_f32_e32 v113, v4, v6
	v_mul_f32_e32 v4, v112, v112
	v_mul_f32_e32 v5, v113, v113
	v_fmac_f32_e32 v4, v157, v157
	v_fmac_f32_e32 v5, v204, v204
	v_add_f32_e32 v130, v4, v5
	ds_read_b128 v[4:7], v102 offset:32
	s_waitcnt lgkmcnt(1)
	v_mfma_f32_32x32x16_bf16 v[16:31], v[16:19], v[0:3], 0
	ds_read_b128 v[146:149], v102 offset:64
	v_cvt_pk_bf16_f32 v145, v157, v112
	v_lshlrev_b32_e32 v112, 16, v78
	v_cvt_pk_bf16_f32 v142, v204, v113
	v_mul_f32_e32 v112, v8, v112
	v_and_b32_e32 v8, 0xffff0000, v79
	v_add_f32_e32 v129, v130, v129
	s_waitcnt lgkmcnt(1)
	v_mfma_f32_32x32x16_bf16 v[16:31], v[4:7], v[72:75], v[16:31]
	v_and_b32_e32 v4, 0xffff0000, v78
	v_add_f32_e32 v5, v128, v9
	v_mul_f32_e32 v78, v5, v4
	v_lshlrev_b32_e32 v4, 16, v79
	v_add_f32_e32 v5, v128, v10
	v_mul_f32_e32 v113, v5, v4
	ds_read_b128 v[4:7], v102 offset:96
	s_waitcnt lgkmcnt(1)
	v_mfma_f32_32x32x16_bf16 v[16:31], v[146:149], v[68:71], v[16:31]
	v_add_f32_e32 v9, v128, v11
	v_mul_f32_e32 v79, v9, v8
	ds_read_b128 v[8:11], v102 offset:128
	v_mul_f32_e32 v130, v78, v78
	v_mul_f32_e32 v131, v79, v79
	v_fmac_f32_e32 v130, v112, v112
	v_fmac_f32_e32 v131, v113, v113
	s_waitcnt lgkmcnt(1)
	v_mfma_f32_32x32x16_bf16 v[16:31], v[4:7], v[64:67], v[16:31]
	v_add_f32_e32 v4, v130, v131
	v_add_f32_e32 v129, v4, v129
	ds_read_b128 v[4:7], v102 offset:160
	v_cvt_pk_bf16_f32 v146, v112, v78
	v_lshlrev_b32_e32 v78, 16, v76
	v_cvt_pk_bf16_f32 v143, v113, v79
	s_waitcnt vmcnt(0)
	v_and_b32_e32 v189, 0xffff0000, v60
	s_waitcnt lgkmcnt(1)
	v_mfma_f32_32x32x16_bf16 v[16:31], v[8:11], v[56:59], v[16:31]
	v_add_f32_e32 v8, v128, v12
	v_mul_f32_e32 v12, v8, v78
	v_and_b32_e32 v8, 0xffff0000, v76
	v_add_f32_e32 v9, v128, v13
	v_mul_f32_e32 v13, v9, v8
	ds_read_b128 v[8:11], v102 offset:192
	v_lshlrev_b32_e32 v76, 16, v77
	s_waitcnt lgkmcnt(1)
	v_mfma_f32_32x32x16_bf16 v[16:31], v[4:7], v[48:51], v[16:31]
	v_add_f32_e32 v4, v128, v14
	v_mul_f32_e32 v14, v4, v76
	v_and_b32_e32 v4, 0xffff0000, v77
	v_add_f32_e32 v5, v128, v15
	v_mul_f32_e32 v15, v5, v4
	ds_read_b128 v[4:7], v102 offset:224
	v_mul_f32_e32 v76, v13, v13
	s_waitcnt lgkmcnt(1)
	v_mfma_f32_32x32x16_bf16 v[16:31], v[8:11], v[44:47], v[16:31]
	v_mul_f32_e32 v8, v15, v15
	v_fmac_f32_e32 v76, v12, v12
	v_fmac_f32_e32 v8, v14, v14
	v_add_f32_e32 v8, v76, v8
	v_add_f32_e32 v8, v8, v129
	v_cvt_pk_bf16_f32 v147, v12, v13
	v_cvt_pk_bf16_f32 v144, v14, v15
	s_waitcnt lgkmcnt(0)
	v_mfma_f32_32x32x16_bf16 v[16:31], v[4:7], v[36:39], v[16:31]
	v_lshlrev_b32_e32 v4, 16, v126
	v_lshlrev_b32_e32 v162, 16, v60
	v_lshlrev_b32_e32 v198, 16, v61
	v_and_b32_e32 v199, 0xffff0000, v61
	v_lshlrev_b32_e32 v200, 16, v62
	v_and_b32_e32 v201, 0xffff0000, v62
	v_lshlrev_b32_e32 v202, 16, v63
	s_nop 4
	v_add_f32_e32 v5, v159, v16
	v_mul_f32_e32 v4, v5, v4
	v_and_b32_e32 v5, 0xffff0000, v126
	v_add_f32_e32 v6, v159, v17
	v_mul_f32_e32 v5, v6, v5
	v_lshlrev_b32_e32 v6, 16, v127
	v_add_f32_e32 v7, v159, v18
	v_mul_f32_e32 v6, v7, v6
	v_and_b32_e32 v7, 0xffff0000, v127
	v_add_f32_e32 v9, v159, v19
	v_mul_f32_e32 v7, v9, v7
	v_mul_f32_e32 v9, v5, v5
	v_fmac_f32_e32 v9, v4, v4
	v_cvt_pk_bf16_f32 v141, v4, v5
	v_lshlrev_b32_e32 v4, 16, v124
	v_add_f32_e32 v5, v159, v20
	v_mul_f32_e32 v20, v5, v4
	v_and_b32_e32 v4, 0xffff0000, v124
	v_add_f32_e32 v5, v159, v21
	v_mul_f32_e32 v10, v7, v7
	v_mul_f32_e32 v21, v5, v4
	v_lshlrev_b32_e32 v4, 16, v125
	v_add_f32_e32 v5, v159, v22
	v_fmac_f32_e32 v10, v6, v6
	v_cvt_pk_bf16_f32 v140, v6, v7
	v_mul_f32_e32 v22, v5, v4
	ds_read_b128 v[4:7], v102 offset:8704
	ds_read_b128 v[16:19], v102 offset:8736
	v_add_f32_e32 v9, v9, v10
	v_add_f32_e32 v76, v8, v9
	v_and_b32_e32 v8, 0xffff0000, v125
	v_add_f32_e32 v9, v159, v23
	v_mul_f32_e32 v23, v9, v8
	v_mul_f32_e32 v8, v21, v21
	v_mul_f32_e32 v9, v23, v23
	v_fmac_f32_e32 v8, v20, v20
	v_fmac_f32_e32 v9, v22, v22
	v_add_f32_e32 v77, v8, v9
	s_waitcnt lgkmcnt(1)
; __device__ __forceinline__ void gmlp_tile(const Ctx& C, int T, LAS unsigned char* lds, int wave, int lane, int tid) {
;     ...
;         bfx8 wf[8];
;         const bf16* wrow = Weff + ((size_t)(mode * 4 + h) * 128 + t) * 128 + 8 * hh;
; #pragma unroll
;         for (int ks = 0; ks < 8; ++ks) wf[ks] = *(const bfx8*)(wrow + 16 * ks);
;         v2u uw[2][4];
; #pragma unroll
;         for (int dbi = 0; dbi < 2; ++dbi)
; #pragma unroll
;             for (int rg = 0; rg < 4; ++rg) uw[dbi][rg] = *(const v2u*)(zt + h * 128 + 32 * (2 * dh + dbi) + 8 * rg + 4 * hh);
;         const float bias = C.in(13)[h * 128 + (mode ? (t & 15) : t)];
;         v4f gvv[8];
;         { const float* gvp = C.in(11) + h * 128 + q * 32;
; #pragma unroll
;           for (int i = 0; i < 8; ++i) gvv[i] = *(const v4f*)(gvp + 4 * i); }
;         __syncthreads();
;         {
;             float v[32]; float s = 0.f;
; #pragma unroll
;             for (int i = 0; i < 4; ++i) { const v4u w = vraw[i];
;                 v[8 * i + 0] = bf_lo(w.x); v[8 * i + 1] = bf_hi(w.x); v[8 * i + 2] = bf_lo(w.y); v[8 * i + 3] = bf_hi(w.y);
;                 v[8 * i + 4] = bf_lo(w.z); v[8 * i + 5] = bf_hi(w.z); v[8 * i + 6] = bf_lo(w.w); v[8 * i + 7] = bf_hi(w.w); }
;             if (h < 3) {
; #pragma unroll
;                 for (int i = 0; i < 4; ++i) vraw[i] = *(const v4u*)(vsrc + (h + 1) * 128 + 8 * i);
;     ...
; #pragma unroll
;         for (int dbi = 0; dbi < 2; ++dbi) {
;             const int db = 2 * dh + dbi;
;             v16f acc;
; #pragma unroll
;             for (int r = 0; r < 16; ++r) acc[r] = 0.f;
; #pragma unroll
;             for (int ks = 0; ks < 8; ++ks) {
;                 const bfx8 va = *(const LAS bfx8*)(VT + (32 * db + tl) * VT_STRIDE + 16 * ks + 8 * hh);
;                 acc = __builtin_amdgcn_mfma_f32_32x32x16_bf16(va, wf[ks], acc, 0, 0, 0);
;             }
; #pragma unroll
;             for (int rg = 0; rg < 4; ++rg) {
;                 const v2u u2 = uw[dbi][rg];
;                 const float o0 = bf_lo(u2.x) * (acc[4 * rg + 0] + bias), o1 = bf_hi(u2.x) * (acc[4 * rg + 1] + bias);
;                 const float o2 = bf_lo(u2.y) * (acc[4 * rg + 2] + bias), o3 = bf_hi(u2.y) * (acc[4 * rg + 3] + bias);
;                 ssq += (o0 * o0 + o1 * o1) + (o2 * o2 + o3 * o3);
;                 outp[h][dbi][2 * rg] = cvt_pk_nv(o0, o1); outp[h][dbi][2 * rg + 1] = cvt_pk_nv(o2, o3);
;             }
	v_mfma_f32_32x32x16_bf16 v[0:15], v[4:7], v[0:3], 0
	v_cvt_pk_bf16_f32 v153, v20, v21
	v_lshlrev_b32_e32 v20, 16, v122
	v_add_f32_e32 v21, v159, v24
	v_cvt_pk_bf16_f32 v150, v22, v23
	v_mul_f32_e32 v24, v21, v20
	ds_read_b128 v[20:23], v102 offset:8768
	v_add_f32_e32 v76, v77, v76
	s_waitcnt lgkmcnt(1)
	v_mfma_f32_32x32x16_bf16 v[0:15], v[16:19], v[72:75], v[0:15]
	v_and_b32_e32 v16, 0xffff0000, v122
	v_add_f32_e32 v17, v159, v25
	v_mul_f32_e32 v25, v17, v16
	v_lshlrev_b32_e32 v16, 16, v123
	v_add_f32_e32 v17, v159, v26
	v_mul_f32_e32 v26, v17, v16
	ds_read_b128 v[16:19], v102 offset:8800
	s_waitcnt lgkmcnt(1)
	v_mfma_f32_32x32x16_bf16 v[0:15], v[20:23], v[68:71], v[0:15]
	v_and_b32_e32 v20, 0xffff0000, v123
	v_add_f32_e32 v21, v159, v27
	v_mul_f32_e32 v27, v21, v20
	ds_read_b128 v[20:23], v102 offset:8832
	v_mul_f32_e32 v68, v25, v25
	v_mul_f32_e32 v69, v27, v27
	v_fmac_f32_e32 v68, v24, v24
	s_waitcnt lgkmcnt(1)
	v_mfma_f32_32x32x16_bf16 v[0:15], v[16:19], v[64:67], v[0:15]
	v_fmac_f32_e32 v69, v26, v26
	v_add_f32_e32 v16, v68, v69
	v_add_f32_e32 v64, v16, v76
	ds_read_b128 v[16:19], v102 offset:8864
	v_cvt_pk_bf16_f32 v154, v24, v25
	v_lshlrev_b32_e32 v24, 16, v118
	v_cvt_pk_bf16_f32 v151, v26, v27
	s_waitcnt lgkmcnt(1)
	v_mfma_f32_32x32x16_bf16 v[0:15], v[20:23], v[56:59], v[0:15]
	v_add_f32_e32 v20, v159, v28
	v_mul_f32_e32 v24, v20, v24
	v_and_b32_e32 v20, 0xffff0000, v118
	v_add_f32_e32 v21, v159, v29
	v_mul_f32_e32 v25, v21, v20
	ds_read_b128 v[20:23], v102 offset:8896
	v_lshlrev_b32_e32 v26, 16, v119
	s_waitcnt lgkmcnt(1)
	v_mfma_f32_32x32x16_bf16 v[0:15], v[16:19], v[48:51], v[0:15]
	v_add_f32_e32 v16, v159, v30
	v_mul_f32_e32 v26, v16, v26
	v_and_b32_e32 v16, 0xffff0000, v119
	v_add_f32_e32 v17, v159, v31
	v_mul_f32_e32 v27, v17, v16
	ds_read_b128 v[16:19], v102 offset:8928
	v_mul_f32_e32 v28, v25, v25
	s_waitcnt lgkmcnt(1)
	v_mfma_f32_32x32x16_bf16 v[0:15], v[20:23], v[44:47], v[0:15]
	v_mul_f32_e32 v20, v27, v27
	v_fmac_f32_e32 v28, v24, v24
	v_fmac_f32_e32 v20, v26, v26
	v_add_f32_e32 v20, v28, v20
	v_add_f32_e32 v20, v20, v64
	v_cvt_pk_bf16_f32 v155, v24, v25
	v_cvt_pk_bf16_f32 v152, v26, v27
	s_waitcnt lgkmcnt(0)
	v_mfma_f32_32x32x16_bf16 v[0:15], v[16:19], v[36:39], v[0:15]
	v_lshlrev_b32_e32 v16, 16, v116
	v_mul_f32_e32 v39, v189, v189
	v_fmac_f32_e32 v39, v162, v162
	v_fmac_f32_e32 v39, v198, v198
	v_fmac_f32_e32 v39, v199, v199
	v_fmac_f32_e32 v39, v200, v200
	v_fmac_f32_e32 v39, v201, v201
	s_nop 4
	v_add_f32_e32 v0, v159, v0
	v_mul_f32_e32 v0, v0, v16
	v_and_b32_e32 v16, 0xffff0000, v116
	v_add_f32_e32 v1, v159, v1
	v_mul_f32_e32 v1, v1, v16
	v_lshlrev_b32_e32 v16, 16, v117
	v_add_f32_e32 v2, v159, v2
	v_mul_f32_e32 v2, v2, v16
	v_and_b32_e32 v16, 0xffff0000, v117
	v_add_f32_e32 v3, v159, v3
	v_mul_f32_e32 v3, v3, v16
	v_mul_f32_e32 v16, v1, v1
	v_mul_f32_e32 v17, v3, v3
	v_fmac_f32_e32 v16, v0, v0
	v_fmac_f32_e32 v17, v2, v2
	v_add_f32_e32 v16, v16, v17
	v_add_f32_e32 v157, v20, v16
	v_add_co_u32_e32 v16, vcc, s40, v104
	v_cvt_pk_bf16_f32 v149, v0, v1
	v_cvt_pk_bf16_f32 v148, v2, v3
	v_add_f32_e32 v4, v159, v4
	s_nop 0
	v_addc_co_u32_e32 v17, vcc, 0, v105, vcc
	global_load_dwordx4 v[0:3], v[16:17], off offset:-3584
	global_load_dwordx4 v[76:79], v[16:17], off offset:-2560
	global_load_dwordx4 v[72:75], v[16:17], off offset:-1536
	global_load_dwordx4 v[68:71], v[16:17], off offset:-512
	global_load_dwordx4 v[64:67], v[16:17], off offset:512
	global_load_dwordx4 v[56:59], v[16:17], off offset:1536
	global_load_dwordx4 v[48:51], v[16:17], off offset:2560
	global_load_dwordx4 v[44:47], v[16:17], off offset:3584
	global_load_dwordx2 v[130:131], v[106:107], off offset:512
	global_load_dwordx2 v[128:129], v[106:107], off offset:528
	global_load_dwordx2 v[126:127], v[106:107], off offset:544
	global_load_dwordx2 v[124:125], v[106:107], off offset:560
	global_load_dwordx2 v[122:123], v[106:107], off offset:576
	global_load_dwordx2 v[118:119], v[106:107], off offset:592
	global_load_dwordx2 v[116:117], v[106:107], off offset:608
	global_load_dwordx2 v[112:113], v[106:107], off offset:624
	s_load_dwordx2 s[0:1], s[0:1], 0x68
	v_lshlrev_b32_e32 v16, 16, v120
	v_mul_f32_e32 v158, v4, v16
	v_and_b32_e32 v203, 0xffff0000, v63
	v_fmac_f32_e32 v39, v202, v202
	s_waitcnt lgkmcnt(0)
	global_load_dword v163, v156, s[0:1] offset:1024
	s_mov_b64 s[0:1], s[80:81]
	s_load_dwordx2 s[28:29], s[0:1], 0x58
	s_waitcnt lgkmcnt(0)
	global_load_dwordx4 v[16:19], v139, s[28:29] offset:1072
	global_load_dwordx4 v[20:23], v139, s[28:29] offset:1056
	global_load_dwordx4 v[24:27], v139, s[28:29] offset:1040
	global_load_dwordx4 v[28:31], v139, s[28:29] offset:1024
	v_lshlrev_b32_e32 v204, 16, v52
	v_fmac_f32_e32 v39, v203, v203
	v_and_b32_e32 v205, 0xffff0000, v52
	v_fmac_f32_e32 v39, v204, v204
	v_lshlrev_b32_e32 v206, 16, v53
	v_fmac_f32_e32 v39, v205, v205
	v_and_b32_e32 v207, 0xffff0000, v53
	v_fmac_f32_e32 v39, v206, v206
	v_lshlrev_b32_e32 v208, 16, v54
	v_fmac_f32_e32 v39, v207, v207
	v_and_b32_e32 v209, 0xffff0000, v54
	v_fmac_f32_e32 v39, v208, v208
	v_lshlrev_b32_e32 v210, 16, v55
	v_fmac_f32_e32 v39, v209, v209
	v_and_b32_e32 v211, 0xffff0000, v55
	v_fmac_f32_e32 v39, v210, v210
	v_lshlrev_b32_e32 v212, 16, v40
	v_fmac_f32_e32 v39, v211, v211
	v_and_b32_e32 v213, 0xffff0000, v40
	v_fmac_f32_e32 v39, v212, v212
	v_lshlrev_b32_e32 v214, 16, v41
	v_fmac_f32_e32 v39, v213, v213
	v_and_b32_e32 v215, 0xffff0000, v41
	v_fmac_f32_e32 v39, v214, v214
	v_lshlrev_b32_e32 v216, 16, v42
	v_fmac_f32_e32 v39, v215, v215
	v_and_b32_e32 v217, 0xffff0000, v42
	v_fmac_f32_e32 v39, v216, v216
	v_and_b32_e32 v4, 0xffff0000, v120
	v_add_f32_e32 v5, v159, v5
	v_lshlrev_b32_e32 v218, 16, v43
	v_fmac_f32_e32 v39, v217, v217
	v_mul_f32_e32 v120, v5, v4
	v_and_b32_e32 v219, 0xffff0000, v43
	v_fmac_f32_e32 v39, v218, v218
	v_and_b32_e32 v4, 0xffff0000, v32
	v_lshlrev_b32_e32 v5, 16, v32
	global_load_dwordx4 v[40:43], v139, s[28:29] offset:1136
	global_load_dwordx4 v[164:167], v139, s[28:29] offset:1120
	global_load_dwordx4 v[178:181], v139, s[28:29] offset:1104
	global_load_dwordx4 v[190:193], v139, s[28:29] offset:1088
	v_fmac_f32_e32 v39, v219, v219
	v_pk_mul_f32 v[36:37], v[4:5], v[4:5]
	v_and_b32_e32 v160, 0xffff0000, v33
	v_add_f32_e32 v32, v37, v39
	v_lshlrev_b32_e32 v161, 16, v33
	v_add_f32_e32 v36, v36, v32
	v_pk_mul_f32 v[32:33], v[160:161], v[160:161]
	v_and_b32_e32 v194, 0xffff0000, v34
	v_add_f32_e32 v33, v33, v36
	v_lshlrev_b32_e32 v195, 16, v34
	v_add_f32_e32 v36, v32, v33
	v_pk_mul_f32 v[32:33], v[194:195], v[194:195]
	v_and_b32_e32 v196, 0xffff0000, v35
	v_add_f32_e32 v33, v33, v36
	v_lshlrev_b32_e32 v197, 16, v35
	v_add_f32_e32 v34, v32, v33
	v_pk_mul_f32 v[32:33], v[196:197], v[196:197]
	v_lshlrev_b32_e32 v38, 16, v121
	v_add_f32_e32 v33, v33, v34
	v_add_f32_e32 v32, v32, v33
	ds_bpermute_b32 v33, v183, v32
	v_add_f32_e32 v6, v159, v6
	v_mul_f32_e32 v220, v6, v38
	v_and_b32_e32 v6, 0xffff0000, v121
	s_waitcnt lgkmcnt(0)
	v_add_f32_e32 v32, v32, v33
	ds_bpermute_b32 v33, v184, v32
	s_barrier
; __device__ __forceinline__ float bf_lo(unsigned w) { return __uint_as_float(w << 16); }
; __device__ __forceinline__ float bf_hi(unsigned w) { return __uint_as_float(w & 0xffff0000u); }
; __device__ __forceinline__ bf16 f2bf(float f) { return (bf16)(cvt_pk_nv(f, 0.f) & 0xffffu); }
; __device__ __forceinline__ void gmlp_tile(const Ctx& C, int T, LAS unsigned char* lds, int wave, int lane, int tid) {
;     ...
;         __syncthreads();
;         {
;             float v[32]; float s = 0.f;
; #pragma unroll
;             for (int i = 0; i < 4; ++i) { const v4u w = vraw[i];
;                 v[8 * i + 0] = bf_lo(w.x); v[8 * i + 1] = bf_hi(w.x); v[8 * i + 2] = bf_lo(w.y); v[8 * i + 3] = bf_hi(w.y);
;                 v[8 * i + 4] = bf_lo(w.z); v[8 * i + 5] = bf_hi(w.z); v[8 * i + 6] = bf_lo(w.w); v[8 * i + 7] = bf_hi(w.w); }
;             if (h < 3) {
; #pragma unroll
;                 for (int i = 0; i < 4; ++i) vraw[i] = *(const v4u*)(vsrc + (h + 1) * 128 + 8 * i);
;             }
; #pragma unroll
;             for (int i = 0; i < 32; ++i) s += v[i] * v[i];
;             s += __shfl_xor(s, 1); s += __shfl_xor(s, 2);
;             const float r = rsqrtf(s * (1.f / 128.f) + EPS);
; #pragma unroll
;             for (int i = 0; i < 32; ++i) { v[i] = v[i] * r * gvv[i >> 2][i & 3]; VT[(q * 32 + i) * VT_STRIDE + row] = f2bf(v[i]); }
	s_waitcnt lgkmcnt(0)
	v_add_f32_e32 v8, v159, v8
	s_mov_b64 s[0:1], s[80:81]
	v_add_f32_e32 v32, v32, v33
	v_fmamk_f32 v32, v32, 0x3c000000, v177
	v_mul_f32_e32 v33, 0x4b800000, v32
	v_cmp_gt_f32_e32 vcc, s38, v32
	s_nop 1
	v_cndmask_b32_e32 v32, v32, v33, vcc
	v_rsq_f32_e32 v121, v32
	global_load_dwordx4 v[36:39], v[108:109], off offset:768
	global_load_dwordx4 v[52:55], v[108:109], off offset:784
	global_load_dwordx4 v[32:35], v[108:109], off offset:816
	global_load_dwordx4 v[60:63], v[108:109], off offset:800
	v_mul_f32_e32 v108, 0x45800000, v121
	v_cndmask_b32_e32 v108, v121, v108, vcc
	v_mul_f32_e32 v109, v108, v162
	s_waitcnt vmcnt(8)
	v_mul_f32_e32 v28, v28, v109
	v_cvt_pk_bf16_f32 v28, v28, v83
	ds_write_b16 v174, v28
	v_mul_f32_e32 v28, v108, v189
	v_mul_f32_e32 v28, v29, v28
	v_cvt_pk_bf16_f32 v28, v28, v83
	ds_write_b16 v174, v28 offset:272
	v_mul_f32_e32 v28, v108, v198
	v_mul_f32_e32 v28, v30, v28
	v_cvt_pk_bf16_f32 v28, v28, v83
	ds_write_b16 v174, v28 offset:544
	v_mul_f32_e32 v28, v108, v199
	v_mul_f32_e32 v28, v31, v28
	v_cvt_pk_bf16_f32 v28, v28, v83
	ds_write_b16 v174, v28 offset:816
	v_mul_f32_e32 v28, v108, v200
	v_mul_f32_e32 v24, v24, v28
	v_cvt_pk_bf16_f32 v24, v24, v83
	ds_write_b16 v174, v24 offset:1088
	v_mul_f32_e32 v24, v108, v201
	v_mul_f32_e32 v24, v25, v24
	v_cvt_pk_bf16_f32 v24, v24, v83
	ds_write_b16 v174, v24 offset:1360
	v_mul_f32_e32 v24, v108, v202
	v_mul_f32_e32 v24, v26, v24
	v_cvt_pk_bf16_f32 v24, v24, v83
	ds_write_b16 v174, v24 offset:1632
	v_mul_f32_e32 v24, v108, v203
	v_mul_f32_e32 v24, v27, v24
	v_cvt_pk_bf16_f32 v24, v24, v83
	ds_write_b16 v174, v24 offset:1904
	v_mul_f32_e32 v24, v108, v204
	v_mul_f32_e32 v20, v20, v24
	v_cvt_pk_bf16_f32 v20, v20, v83
	ds_write_b16 v174, v20 offset:2176
	v_mul_f32_e32 v20, v108, v205
	v_mul_f32_e32 v20, v21, v20
	v_cvt_pk_bf16_f32 v20, v20, v83
	ds_write_b16 v174, v20 offset:2448
	v_mul_f32_e32 v20, v108, v206
	v_mul_f32_e32 v20, v22, v20
	v_cvt_pk_bf16_f32 v20, v20, v83
	ds_write_b16 v174, v20 offset:2720
	v_mul_f32_e32 v20, v108, v207
	v_mul_f32_e32 v20, v23, v20
	v_cvt_pk_bf16_f32 v20, v20, v83
	ds_write_b16 v174, v20 offset:2992
	v_mul_f32_e32 v20, v108, v208
	v_mul_f32_e32 v16, v16, v20
	v_cvt_pk_bf16_f32 v16, v16, v83
	ds_write_b16 v174, v16 offset:3264
	v_mul_f32_e32 v16, v108, v209
	v_mul_f32_e32 v16, v17, v16
	v_cvt_pk_bf16_f32 v16, v16, v83
	ds_write_b16 v174, v16 offset:3536
	v_mul_f32_e32 v16, v108, v210
	v_mul_f32_e32 v16, v18, v16
	v_cvt_pk_bf16_f32 v16, v16, v83
	ds_write_b16 v174, v16 offset:3808
	v_mul_f32_e32 v16, v108, v211
	v_mul_f32_e32 v16, v19, v16
	v_cvt_pk_bf16_f32 v16, v16, v83
	ds_write_b16 v174, v16 offset:4080
	v_mul_f32_e32 v16, v108, v212
	s_waitcnt vmcnt(4)
	v_mul_f32_e32 v16, v190, v16
	v_cvt_pk_bf16_f32 v16, v16, v83
	ds_write_b16 v174, v16 offset:4352
	v_mul_f32_e32 v16, v108, v213
	v_mul_f32_e32 v16, v191, v16
	v_mul_f32_e32 v4, v108, v4
	v_cvt_pk_bf16_f32 v16, v16, v83
	v_mul_f32_e32 v4, v165, v4
	ds_write_b16 v174, v16 offset:4624
	v_mul_f32_e32 v16, v108, v214
	v_cvt_pk_bf16_f32 v4, v4, v83
	v_mul_f32_e32 v16, v192, v16
	ds_write_b16 v174, v4 offset:6800
	v_mul_f32_e32 v4, v108, v161
	v_cvt_pk_bf16_f32 v16, v16, v83
	v_mul_f32_e32 v4, v166, v4
	ds_write_b16 v174, v16 offset:4896
	v_mul_f32_e32 v16, v108, v215
	v_cvt_pk_bf16_f32 v4, v4, v83
	v_mul_f32_e32 v16, v193, v16
	ds_write_b16 v174, v4 offset:7072
	v_mul_f32_e32 v4, v108, v160
	v_cvt_pk_bf16_f32 v16, v16, v83
	v_mul_f32_e32 v4, v167, v4
	ds_write_b16 v174, v16 offset:5168
	v_mul_f32_e32 v16, v108, v216
	v_cvt_pk_bf16_f32 v4, v4, v83
	v_mul_f32_e32 v16, v178, v16
	ds_write_b16 v174, v4 offset:7344
	v_mul_f32_e32 v4, v108, v195
	v_cvt_pk_bf16_f32 v16, v16, v83
	v_mul_f32_e32 v4, v40, v4
	ds_write_b16 v174, v16 offset:5440
	v_mul_f32_e32 v16, v108, v217
	v_cvt_pk_bf16_f32 v4, v4, v83
	v_mul_f32_e32 v16, v179, v16
	ds_write_b16 v174, v4 offset:7616
	v_mul_f32_e32 v4, v108, v194
	v_cvt_pk_bf16_f32 v16, v16, v83
	v_mul_f32_e32 v4, v41, v4
	ds_write_b16 v174, v16 offset:5712
	v_mul_f32_e32 v16, v108, v218
	v_cvt_pk_bf16_f32 v4, v4, v83
	v_mul_f32_e32 v16, v180, v16
	ds_write_b16 v174, v4 offset:7888
	v_mul_f32_e32 v4, v108, v197
	v_cvt_pk_bf16_f32 v16, v16, v83
	v_mul_f32_e32 v4, v42, v4
	ds_write_b16 v174, v16 offset:5984
	v_mul_f32_e32 v16, v108, v219
	v_cvt_pk_bf16_f32 v4, v4, v83
	v_mul_f32_e32 v16, v181, v16
	v_mul_f32_e32 v5, v108, v5
	ds_write_b16 v174, v4 offset:8160
	v_mul_f32_e32 v4, v108, v196
	v_cvt_pk_bf16_f32 v16, v16, v83
	v_mul_f32_e32 v5, v164, v5
	v_mul_f32_e32 v4, v43, v4
	ds_write_b16 v174, v16 offset:6256
	v_cvt_pk_bf16_f32 v5, v5, v83
	ds_write_b16 v174, v5 offset:6528
	v_cvt_pk_bf16_f32 v4, v4, v83
	ds_write_b16 v174, v4 offset:8432
	s_waitcnt lgkmcnt(0)
	s_barrier
; __device__ __forceinline__ float bf_lo(unsigned w) { return __uint_as_float(w << 16); }
; __device__ __forceinline__ float bf_hi(unsigned w) { return __uint_as_float(w & 0xffff0000u); }
; #define LAS __attribute__((address_space(3)))
; __device__ __forceinline__ unsigned cvt_pk_nv(float lo, float hi) { unsigned r; asm("v_cvt_pk_bf16_f32 %0, %1, %2" : "=v"(r) : "v"(lo), "v"(hi)); return r; }
; __device__ __forceinline__ void gmlp_tile(const Ctx& C, int T, LAS unsigned char* lds, int wave, int lane, int tid) {
;     ...
; #pragma unroll
;         for (int dbi = 0; dbi < 2; ++dbi) {
;             const int db = 2 * dh + dbi;
;             v16f acc;
; #pragma unroll
;             for (int r = 0; r < 16; ++r) acc[r] = 0.f;
; #pragma unroll
;             for (int ks = 0; ks < 8; ++ks) {
;                 const bfx8 va = *(const LAS bfx8*)(VT + (32 * db + tl) * VT_STRIDE + 16 * ks + 8 * hh);
;                 acc = __builtin_amdgcn_mfma_f32_32x32x16_bf16(va, wf[ks], acc, 0, 0, 0);
;             }
; #pragma unroll
;             for (int rg = 0; rg < 4; ++rg) {
;                 const v2u u2 = uw[dbi][rg];
;                 const float o0 = bf_lo(u2.x) * (acc[4 * rg + 0] + bias), o1 = bf_hi(u2.x) * (acc[4 * rg + 1] + bias);
;                 const float o2 = bf_lo(u2.y) * (acc[4 * rg + 2] + bias), o3 = bf_hi(u2.y) * (acc[4 * rg + 3] + bias);
;                 ssq += (o0 * o0 + o1 * o1) + (o2 * o2 + o3 * o3);
;                 outp[h][dbi][2 * rg] = cvt_pk_nv(o0, o1); outp[h][dbi][2 * rg + 1] = cvt_pk_nv(o2, o3);
;             }
	ds_read_b128 v[16:19], v102
	v_add_f32_e32 v4, v159, v7
	v_mul_f32_e32 v40, v4, v6
	v_mul_f32_e32 v4, v120, v120
	v_mul_f32_e32 v5, v40, v40
	v_fmac_f32_e32 v4, v158, v158
	v_fmac_f32_e32 v5, v220, v220
	v_add_f32_e32 v41, v4, v5
	ds_read_b128 v[4:7], v102 offset:32
	s_waitcnt lgkmcnt(1)
	v_mfma_f32_32x32x16_bf16 v[16:31], v[16:19], v[0:3], 0
	v_add_f32_e32 v108, v41, v157
	v_cvt_pk_bf16_f32 v157, v220, v40
	v_lshlrev_b32_e32 v40, 16, v114
	v_mul_f32_e32 v109, v8, v40
	ds_read_b128 v[40:43], v102 offset:64
	v_cvt_pk_bf16_f32 v160, v158, v120
	v_and_b32_e32 v8, 0xffff0000, v115
	s_waitcnt lgkmcnt(1)
	v_mfma_f32_32x32x16_bf16 v[16:31], v[4:7], v[76:79], v[16:31]
	v_and_b32_e32 v4, 0xffff0000, v114
	v_add_f32_e32 v5, v159, v9
	v_mul_f32_e32 v114, v5, v4
	v_lshlrev_b32_e32 v4, 16, v115
	v_add_f32_e32 v5, v159, v10
	v_mul_f32_e32 v120, v5, v4
	ds_read_b128 v[4:7], v102 offset:96
	s_waitcnt lgkmcnt(1)
	v_mfma_f32_32x32x16_bf16 v[16:31], v[40:43], v[72:75], v[16:31]
	v_add_f32_e32 v9, v159, v11
	v_mul_f32_e32 v40, v9, v8
	ds_read_b128 v[8:11], v102 offset:128
	v_mul_f32_e32 v41, v114, v114
	v_mul_f32_e32 v42, v40, v40
	v_fmac_f32_e32 v41, v109, v109
	v_fmac_f32_e32 v42, v120, v120
	s_waitcnt lgkmcnt(1)
	v_mfma_f32_32x32x16_bf16 v[16:31], v[4:7], v[68:71], v[16:31]
	v_add_f32_e32 v4, v41, v42
	v_add_f32_e32 v41, v4, v108
	ds_read_b128 v[4:7], v102 offset:160
	v_cvt_pk_bf16_f32 v158, v120, v40
	v_lshlrev_b32_e32 v40, 16, v110
	v_cvt_pk_bf16_f32 v161, v109, v114
	s_waitcnt vmcnt(3)
	v_and_b32_e32 v212, 0xffff0000, v36
	s_waitcnt lgkmcnt(1)
	v_mfma_f32_32x32x16_bf16 v[16:31], v[8:11], v[64:67], v[16:31]
	v_add_f32_e32 v8, v159, v12
	v_mul_f32_e32 v12, v8, v40
	v_and_b32_e32 v8, 0xffff0000, v110
	v_add_f32_e32 v9, v159, v13
	v_mul_f32_e32 v13, v9, v8
	ds_read_b128 v[8:11], v102 offset:192
	v_lshlrev_b32_e32 v40, 16, v111
	s_waitcnt lgkmcnt(1)
	v_mfma_f32_32x32x16_bf16 v[16:31], v[4:7], v[56:59], v[16:31]
	v_add_f32_e32 v4, v159, v14
	v_mul_f32_e32 v14, v4, v40
	v_and_b32_e32 v4, 0xffff0000, v111
	v_add_f32_e32 v5, v159, v15
	v_mul_f32_e32 v15, v5, v4
	ds_read_b128 v[4:7], v102 offset:224
	v_mul_f32_e32 v40, v13, v13
	s_waitcnt lgkmcnt(1)
	v_mfma_f32_32x32x16_bf16 v[16:31], v[8:11], v[48:51], v[16:31]
	v_mul_f32_e32 v8, v15, v15
	v_fmac_f32_e32 v40, v12, v12
	v_fmac_f32_e32 v8, v14, v14
	v_add_f32_e32 v8, v40, v8
	v_add_f32_e32 v8, v8, v41
	v_cvt_pk_bf16_f32 v162, v12, v13
	v_cvt_pk_bf16_f32 v159, v14, v15
	s_waitcnt lgkmcnt(0)
	v_mfma_f32_32x32x16_bf16 v[16:31], v[4:7], v[44:47], v[16:31]
	v_lshlrev_b32_e32 v4, 16, v130
	v_and_b32_e32 v208, 0xffff0000, v38
	v_lshlrev_b32_e32 v209, 16, v38
	v_lshlrev_b32_e32 v213, 16, v36
	v_mul_f32_e32 v38, v212, v212
	v_lshlrev_b32_e32 v211, 16, v37
	v_fmac_f32_e32 v38, v213, v213
	s_nop 4
	v_add_f32_e32 v5, v163, v16
	v_mul_f32_e32 v4, v5, v4
	v_and_b32_e32 v5, 0xffff0000, v130
	v_add_f32_e32 v6, v163, v17
	v_mul_f32_e32 v5, v6, v5
	v_lshlrev_b32_e32 v6, 16, v131
	v_add_f32_e32 v7, v163, v18
	v_mul_f32_e32 v6, v7, v6
	v_and_b32_e32 v7, 0xffff0000, v131
	v_add_f32_e32 v9, v163, v19
	v_mul_f32_e32 v7, v9, v7
	v_mul_f32_e32 v9, v5, v5
	v_fmac_f32_e32 v9, v4, v4
	v_cvt_pk_bf16_f32 v131, v4, v5
	v_lshlrev_b32_e32 v4, 16, v128
	v_add_f32_e32 v5, v163, v20
	v_mul_f32_e32 v20, v5, v4
	v_and_b32_e32 v4, 0xffff0000, v128
	v_add_f32_e32 v5, v163, v21
	v_mul_f32_e32 v10, v7, v7
	v_mul_f32_e32 v21, v5, v4
	v_lshlrev_b32_e32 v4, 16, v129
	v_add_f32_e32 v5, v163, v22
	v_fmac_f32_e32 v10, v6, v6
	v_cvt_pk_bf16_f32 v130, v6, v7
	v_mul_f32_e32 v22, v5, v4
	ds_read_b128 v[4:7], v102 offset:8704
	ds_read_b128 v[16:19], v102 offset:8736
	v_add_f32_e32 v9, v9, v10
	v_add_f32_e32 v40, v8, v9
	v_and_b32_e32 v8, 0xffff0000, v129
	v_add_f32_e32 v9, v163, v23
	v_mul_f32_e32 v23, v9, v8
	v_mul_f32_e32 v8, v21, v21
	v_mul_f32_e32 v9, v23, v23
	v_fmac_f32_e32 v8, v20, v20
	v_fmac_f32_e32 v9, v22, v22
	v_add_f32_e32 v41, v8, v9
	s_waitcnt lgkmcnt(1)
	v_mfma_f32_32x32x16_bf16 v[0:15], v[4:7], v[0:3], 0
	v_cvt_pk_bf16_f32 v129, v20, v21
	v_lshlrev_b32_e32 v20, 16, v126
	v_add_f32_e32 v21, v163, v24
	v_cvt_pk_bf16_f32 v128, v22, v23
	v_mul_f32_e32 v24, v21, v20
	ds_read_b128 v[20:23], v102 offset:8768
	v_add_f32_e32 v40, v41, v40
	s_waitcnt lgkmcnt(1)
	v_mfma_f32_32x32x16_bf16 v[0:15], v[16:19], v[76:79], v[0:15]
	v_and_b32_e32 v16, 0xffff0000, v126
	v_add_f32_e32 v17, v163, v25
	v_mul_f32_e32 v25, v17, v16
	v_lshlrev_b32_e32 v16, 16, v127
	v_add_f32_e32 v17, v163, v26
	v_mul_f32_e32 v26, v17, v16
	ds_read_b128 v[16:19], v102 offset:8800
	s_waitcnt lgkmcnt(1)
	v_mfma_f32_32x32x16_bf16 v[0:15], v[20:23], v[72:75], v[0:15]
	v_and_b32_e32 v20, 0xffff0000, v127
	v_add_f32_e32 v21, v163, v27
	v_mul_f32_e32 v27, v21, v20
	ds_read_b128 v[20:23], v102 offset:8832
	v_mul_f32_e32 v41, v25, v25
	v_mul_f32_e32 v42, v27, v27
	v_fmac_f32_e32 v41, v24, v24
	s_waitcnt lgkmcnt(1)
	v_mfma_f32_32x32x16_bf16 v[0:15], v[16:19], v[68:71], v[0:15]
	v_fmac_f32_e32 v42, v26, v26
	v_add_f32_e32 v16, v41, v42
	v_add_f32_e32 v40, v16, v40
	ds_read_b128 v[16:19], v102 offset:8864
	v_cvt_pk_bf16_f32 v127, v24, v25
	v_lshlrev_b32_e32 v24, 16, v124
	v_cvt_pk_bf16_f32 v126, v26, v27
	s_waitcnt lgkmcnt(1)
	v_mfma_f32_32x32x16_bf16 v[0:15], v[20:23], v[64:67], v[0:15]
	v_add_f32_e32 v20, v163, v28
	v_mul_f32_e32 v24, v20, v24
	v_and_b32_e32 v20, 0xffff0000, v124
	v_add_f32_e32 v21, v163, v29
	v_mul_f32_e32 v25, v21, v20
	ds_read_b128 v[20:23], v102 offset:8896
	v_lshlrev_b32_e32 v26, 16, v125
	s_waitcnt lgkmcnt(1)
	v_mfma_f32_32x32x16_bf16 v[0:15], v[16:19], v[56:59], v[0:15]
	v_add_f32_e32 v16, v163, v30
	v_mul_f32_e32 v26, v16, v26
	v_and_b32_e32 v16, 0xffff0000, v125
	v_add_f32_e32 v17, v163, v31
	v_mul_f32_e32 v27, v17, v16
	ds_read_b128 v[16:19], v102 offset:8928
	v_mul_f32_e32 v28, v25, v25
	s_waitcnt lgkmcnt(1)
; __device__ __forceinline__ float bf_lo(unsigned w) { return __uint_as_float(w << 16); }
; __device__ __forceinline__ void gmlp_tile(const Ctx& C, int T, LAS unsigned char* lds, int wave, int lane, int tid) {
;     ...
;         bfx8 wf[8];
;         const bf16* wrow = Weff + ((size_t)(mode * 4 + h) * 128 + t) * 128 + 8 * hh;
; #pragma unroll
;         for (int ks = 0; ks < 8; ++ks) wf[ks] = *(const bfx8*)(wrow + 16 * ks);
;         v2u uw[2][4];
; #pragma unroll
;         for (int dbi = 0; dbi < 2; ++dbi)
; #pragma unroll
;             for (int rg = 0; rg < 4; ++rg) uw[dbi][rg] = *(const v2u*)(zt + h * 128 + 32 * (2 * dh + dbi) + 8 * rg + 4 * hh);
;         const float bias = C.in(13)[h * 128 + (mode ? (t & 15) : t)];
;         v4f gvv[8];
;         { const float* gvp = C.in(11) + h * 128 + q * 32;
; #pragma unroll
;           for (int i = 0; i < 8; ++i) gvv[i] = *(const v4f*)(gvp + 4 * i); }
;         __syncthreads();
;         {
;             float v[32]; float s = 0.f;
; #pragma unroll
;             for (int i = 0; i < 4; ++i) { const v4u w = vraw[i];
;                 v[8 * i + 0] = bf_lo(w.x); v[8 * i + 1] = bf_hi(w.x); v[8 * i + 2] = bf_lo(w.y); v[8 * i + 3] = bf_hi(w.y);
;                 v[8 * i + 4] = bf_lo(w.z); v[8 * i + 5] = bf_hi(w.z); v[8 * i + 6] = bf_lo(w.w); v[8 * i + 7] = bf_hi(w.w); }
;             if (h < 3) {
; #pragma unroll
;                 for (int i = 0; i < 4; ++i) vraw[i] = *(const v4u*)(vsrc + (h + 1) * 128 + 8 * i);
;             }
; #pragma unroll
;             for (int i = 0; i < 32; ++i) s += v[i] * v[i];
;             s += __shfl_xor(s, 1); s += __shfl_xor(s, 2);
;             const float r = rsqrtf(s * (1.f / 128.f) + EPS);
; #pragma unroll
;             for (int i = 0; i < 32; ++i) { v[i] = v[i] * r * gvv[i >> 2][i & 3]; VT[(q * 32 + i) * VT_STRIDE + row] = f2bf(v[i]); }
;     ...
;             for (int rg = 0; rg < 4; ++rg) {
;                 const v2u u2 = uw[dbi][rg];
;                 const float o0 = bf_lo(u2.x) * (acc[4 * rg + 0] + bias), o1 = bf_hi(u2.x) * (acc[4 * rg + 1] + bias);
;                 const float o2 = bf_lo(u2.y) * (acc[4 * rg + 2] + bias), o3 = bf_hi(u2.y) * (acc[4 * rg + 3] + bias);
;                 ssq += (o0 * o0 + o1 * o1) + (o2 * o2 + o3 * o3);
;                 outp[h][dbi][2 * rg] = cvt_pk_nv(o0, o1); outp[h][dbi][2 * rg + 1] = cvt_pk_nv(o2, o3);
;             }
	v_mfma_f32_32x32x16_bf16 v[0:15], v[20:23], v[48:51], v[0:15]
	v_mul_f32_e32 v20, v27, v27
	v_fmac_f32_e32 v28, v24, v24
	v_fmac_f32_e32 v20, v26, v26
	v_add_f32_e32 v20, v28, v20
	v_add_f32_e32 v20, v20, v40
	v_cvt_pk_bf16_f32 v125, v24, v25
	v_cvt_pk_bf16_f32 v124, v26, v27
	s_waitcnt lgkmcnt(0)
	v_mfma_f32_32x32x16_bf16 v[0:15], v[16:19], v[44:47], v[0:15]
	v_lshlrev_b32_e32 v16, 16, v122
	v_and_b32_e32 v210, 0xffff0000, v37
	v_fmac_f32_e32 v38, v211, v211
	v_fmac_f32_e32 v38, v210, v210
	v_fmac_f32_e32 v38, v209, v209
	v_lshlrev_b32_e32 v207, 16, v39
	v_fmac_f32_e32 v38, v208, v208
	s_nop 4
	v_add_f32_e32 v0, v163, v0
	v_mul_f32_e32 v18, v0, v16
	v_and_b32_e32 v0, 0xffff0000, v122
	v_add_f32_e32 v1, v163, v1
	v_mul_f32_e32 v19, v1, v0
	v_lshlrev_b32_e32 v0, 16, v123
	v_add_f32_e32 v1, v163, v2
	v_mul_f32_e32 v21, v1, v0
	v_and_b32_e32 v0, 0xffff0000, v123
	v_add_f32_e32 v1, v163, v3
	v_mul_f32_e32 v22, v1, v0
	v_mul_f32_e32 v0, v19, v19
	v_mul_f32_e32 v1, v22, v22
	v_add_co_u32_e32 v16, vcc, s41, v104
	v_fmac_f32_e32 v0, v18, v18
	v_fmac_f32_e32 v1, v21, v21
	v_addc_co_u32_e32 v17, vcc, 0, v105, vcc
	v_add_f32_e32 v23, v0, v1
	global_load_dwordx4 v[0:3], v[16:17], off offset:-3584
	global_load_dwordx4 v[72:75], v[16:17], off offset:-2560
	global_load_dwordx4 v[68:71], v[16:17], off offset:-1536
	global_load_dwordx4 v[64:67], v[16:17], off offset:-512
	global_load_dwordx4 v[56:59], v[16:17], off offset:512
	global_load_dwordx4 v[48:51], v[16:17], off offset:1536
	global_load_dwordx4 v[44:47], v[16:17], off offset:2560
	global_load_dwordx4 v[40:43], v[16:17], off offset:3584
	global_load_dwordx2 v[122:123], v[106:107], off offset:768
	global_load_dwordx2 v[120:121], v[106:107], off offset:784
	global_load_dwordx2 v[114:115], v[106:107], off offset:800
	global_load_dwordx2 v[110:111], v[106:107], off offset:816
	global_load_dwordx2 v[108:109], v[106:107], off offset:832
	global_load_dwordx2 v[104:105], v[106:107], off offset:848
	global_load_dwordx2 v[78:79], v[106:107], off offset:864
	global_load_dwordx2 v[76:77], v[106:107], off offset:880
	s_load_dwordx2 s[0:1], s[0:1], 0x68
	v_lshlrev_b32_e32 v16, 16, v118
	v_add_f32_e32 v4, v163, v4
	v_add_f32_e32 v180, v20, v23
	v_cvt_pk_bf16_f32 v107, v18, v19
	s_waitcnt lgkmcnt(0)
	global_load_dword v156, v156, s[0:1] offset:1536
	s_mov_b64 s[0:1], s[80:81]
	s_load_dwordx2 s[28:29], s[0:1], 0x58
	v_cvt_pk_bf16_f32 v106, v21, v22
	v_mul_f32_e32 v181, v4, v16
	s_waitcnt lgkmcnt(0)
	global_load_dwordx4 v[16:19], v139, s[28:29] offset:1584
	global_load_dwordx4 v[20:23], v139, s[28:29] offset:1568
	global_load_dwordx4 v[24:27], v139, s[28:29] offset:1552
	global_load_dwordx4 v[28:31], v139, s[28:29] offset:1536
	v_and_b32_e32 v206, 0xffff0000, v39
	v_fmac_f32_e32 v38, v207, v207
	s_waitcnt vmcnt(23)
	v_lshlrev_b32_e32 v205, 16, v52
	v_fmac_f32_e32 v38, v206, v206
	v_and_b32_e32 v204, 0xffff0000, v52
	v_fmac_f32_e32 v38, v205, v205
	v_lshlrev_b32_e32 v203, 16, v53
	v_fmac_f32_e32 v38, v204, v204
	v_and_b32_e32 v202, 0xffff0000, v53
	v_fmac_f32_e32 v38, v203, v203
	v_lshlrev_b32_e32 v201, 16, v54
	v_fmac_f32_e32 v38, v202, v202
	v_and_b32_e32 v200, 0xffff0000, v54
	v_fmac_f32_e32 v38, v201, v201
	v_lshlrev_b32_e32 v199, 16, v55
	v_fmac_f32_e32 v38, v200, v200
	v_and_b32_e32 v198, 0xffff0000, v55
	v_fmac_f32_e32 v38, v199, v199
	s_waitcnt vmcnt(21)
	v_lshlrev_b32_e32 v197, 16, v60
	v_fmac_f32_e32 v38, v198, v198
	v_and_b32_e32 v196, 0xffff0000, v60
	v_fmac_f32_e32 v38, v197, v197
	v_lshlrev_b32_e32 v195, 16, v61
	v_fmac_f32_e32 v38, v196, v196
	v_and_b32_e32 v194, 0xffff0000, v61
	v_fmac_f32_e32 v38, v195, v195
	v_lshlrev_b32_e32 v193, 16, v62
	v_fmac_f32_e32 v38, v194, v194
	v_and_b32_e32 v192, 0xffff0000, v62
	v_fmac_f32_e32 v38, v193, v193
	v_lshlrev_b32_e32 v191, 16, v63
	v_fmac_f32_e32 v38, v192, v192
	v_add_f32_e32 v189, v163, v5
	v_and_b32_e32 v190, 0xffff0000, v63
	v_fmac_f32_e32 v38, v191, v191
	v_and_b32_e32 v4, 0xffff0000, v32
	v_lshlrev_b32_e32 v5, 16, v32
	v_fmac_f32_e32 v38, v190, v190
	v_pk_mul_f32 v[36:37], v[4:5], v[4:5]
	v_and_b32_e32 v164, 0xffff0000, v33
	v_add_f32_e32 v32, v37, v38
	v_lshlrev_b32_e32 v165, 16, v33
	v_add_f32_e32 v36, v36, v32
	v_pk_mul_f32 v[32:33], v[164:165], v[164:165]
	v_and_b32_e32 v166, 0xffff0000, v34
	v_add_f32_e32 v33, v33, v36
	v_lshlrev_b32_e32 v167, 16, v34
	v_add_f32_e32 v36, v32, v33
	v_pk_mul_f32 v[32:33], v[166:167], v[166:167]
	v_and_b32_e32 v178, 0xffff0000, v35
	v_add_f32_e32 v33, v33, v36
	v_lshlrev_b32_e32 v179, 16, v35
	v_add_f32_e32 v34, v32, v33
	v_pk_mul_f32 v[32:33], v[178:179], v[178:179]
	v_and_b32_e32 v118, 0xffff0000, v118
	v_add_f32_e32 v33, v33, v34
	v_add_f32_e32 v32, v32, v33
	ds_bpermute_b32 v33, v183, v32
	v_lshlrev_b32_e32 v34, 16, v119
	v_add_f32_e32 v6, v163, v6
	v_mul_f32_e32 v118, v189, v118
	v_mul_f32_e32 v189, v6, v34
	s_waitcnt lgkmcnt(0)
	v_add_f32_e32 v6, v32, v33
	global_load_dwordx4 v[32:35], v139, s[28:29] offset:1616
	global_load_dwordx4 v[36:39], v139, s[28:29] offset:1600
	global_load_dwordx4 v[52:55], v139, s[28:29] offset:1648
	global_load_dwordx4 v[60:63], v139, s[28:29] offset:1632
	ds_bpermute_b32 v214, v184, v6
	s_waitcnt lgkmcnt(0)
	s_barrier
; __device__ __forceinline__ float bf_lo(unsigned w) { return __uint_as_float(w << 16); }
; __device__ __forceinline__ float bf_hi(unsigned w) { return __uint_as_float(w & 0xffff0000u); }
; __device__ __forceinline__ bf16 f2bf(float f) { return (bf16)(cvt_pk_nv(f, 0.f) & 0xffffu); }
;     __device__ __forceinline__ float* out() const { return (float*)karg_in(33); }
; __device__ __forceinline__ void gmlp_tile(const Ctx& C, int T, LAS unsigned char* lds, int wave, int lane, int tid) {
;     ...
;         __syncthreads();
;         {
;             float v[32]; float s = 0.f;
; #pragma unroll
;             for (int i = 0; i < 4; ++i) { const v4u w = vraw[i];
;                 v[8 * i + 0] = bf_lo(w.x); v[8 * i + 1] = bf_hi(w.x); v[8 * i + 2] = bf_lo(w.y); v[8 * i + 3] = bf_hi(w.y);
;                 v[8 * i + 4] = bf_lo(w.z); v[8 * i + 5] = bf_hi(w.z); v[8 * i + 6] = bf_lo(w.w); v[8 * i + 7] = bf_hi(w.w); }
;             if (h < 3) {
; #pragma unroll
;                 for (int i = 0; i < 4; ++i) vraw[i] = *(const v4u*)(vsrc + (h + 1) * 128 + 8 * i);
;             }
; #pragma unroll
;             for (int i = 0; i < 32; ++i) s += v[i] * v[i];
;             s += __shfl_xor(s, 1); s += __shfl_xor(s, 2);
;             const float r = rsqrtf(s * (1.f / 128.f) + EPS);
; #pragma unroll
;             for (int i = 0; i < 32; ++i) { v[i] = v[i] * r * gvv[i >> 2][i & 3]; VT[(q * 32 + i) * VT_STRIDE + row] = f2bf(v[i]); }
;             if (mode) { float* ov = C.out() + OFF_V_S + (size_t)row * AW + h * 128 + q * 32;
; #pragma unroll
;                 for (int i = 0; i < 8; ++i) *(v4f*)(ov + 4 * i) = (v4f){v[4 * i], v[4 * i + 1], v[4 * i + 2], v[4 * i + 3]}; }
;         }
;         __syncthreads();
	v_and_b32_e32 v119, 0xffff0000, v119
	v_add_f32_e32 v6, v6, v214
	v_fmamk_f32 v6, v6, 0x3c000000, v177
	v_mul_f32_e32 v139, 0x4b800000, v6
	v_cmp_gt_f32_e32 vcc, s38, v6
	v_add_f32_e32 v8, v163, v8
	s_nop 0
	v_cndmask_b32_e32 v6, v6, v139, vcc
	v_rsq_f32_e32 v6, v6
	s_nop 0
	v_mul_f32_e32 v139, 0x45800000, v6
	v_cndmask_b32_e32 v6, v6, v139, vcc
	v_mul_f32_e32 v139, v6, v213
	s_waitcnt vmcnt(4)
	v_mul_f32_e32 v28, v28, v139
	v_cvt_pk_bf16_f32 v28, v28, v83
	ds_write_b16 v174, v28
	v_mul_f32_e32 v28, v6, v212
	v_mul_f32_e32 v28, v29, v28
	v_cvt_pk_bf16_f32 v28, v28, v83
	ds_write_b16 v174, v28 offset:272
	v_mul_f32_e32 v28, v6, v211
	v_mul_f32_e32 v28, v30, v28
	v_cvt_pk_bf16_f32 v28, v28, v83
	ds_write_b16 v174, v28 offset:544
	v_mul_f32_e32 v28, v6, v210
	v_mul_f32_e32 v28, v31, v28
	v_cvt_pk_bf16_f32 v28, v28, v83
	ds_write_b16 v174, v28 offset:816
	v_mul_f32_e32 v28, v6, v209
	v_mul_f32_e32 v24, v24, v28
	v_cvt_pk_bf16_f32 v24, v24, v83
	ds_write_b16 v174, v24 offset:1088
	v_mul_f32_e32 v24, v6, v208
	v_mul_f32_e32 v24, v25, v24
	v_cvt_pk_bf16_f32 v24, v24, v83
	ds_write_b16 v174, v24 offset:1360
	v_mul_f32_e32 v24, v6, v207
	v_mul_f32_e32 v24, v26, v24
	v_cvt_pk_bf16_f32 v24, v24, v83
	ds_write_b16 v174, v24 offset:1632
	v_mul_f32_e32 v24, v6, v206
	v_mul_f32_e32 v24, v27, v24
	v_cvt_pk_bf16_f32 v24, v24, v83
	ds_write_b16 v174, v24 offset:1904
	v_mul_f32_e32 v24, v6, v205
	v_mul_f32_e32 v20, v20, v24
	v_cvt_pk_bf16_f32 v20, v20, v83
	ds_write_b16 v174, v20 offset:2176
	v_mul_f32_e32 v20, v6, v204
	v_mul_f32_e32 v20, v21, v20
	v_cvt_pk_bf16_f32 v20, v20, v83
	ds_write_b16 v174, v20 offset:2448
	v_mul_f32_e32 v20, v6, v203
	v_mul_f32_e32 v20, v22, v20
	v_cvt_pk_bf16_f32 v20, v20, v83
	ds_write_b16 v174, v20 offset:2720
	v_mul_f32_e32 v20, v6, v202
	v_mul_f32_e32 v20, v23, v20
	v_cvt_pk_bf16_f32 v20, v20, v83
	ds_write_b16 v174, v20 offset:2992
	v_mul_f32_e32 v20, v6, v201
	v_mul_f32_e32 v16, v16, v20
	v_cvt_pk_bf16_f32 v16, v16, v83
	ds_write_b16 v174, v16 offset:3264
	v_mul_f32_e32 v16, v6, v200
	v_mul_f32_e32 v16, v17, v16
	v_cvt_pk_bf16_f32 v16, v16, v83
	ds_write_b16 v174, v16 offset:3536
	v_mul_f32_e32 v16, v6, v199
	v_mul_f32_e32 v16, v18, v16
	v_cvt_pk_bf16_f32 v16, v16, v83
	ds_write_b16 v174, v16 offset:3808
	v_mul_f32_e32 v16, v6, v198
	v_mul_f32_e32 v16, v19, v16
	v_cvt_pk_bf16_f32 v16, v16, v83
	ds_write_b16 v174, v16 offset:4080
	v_mul_f32_e32 v16, v6, v197
	s_waitcnt vmcnt(2)
	v_mul_f32_e32 v16, v36, v16
	v_cvt_pk_bf16_f32 v16, v16, v83
	ds_write_b16 v174, v16 offset:4352
	v_mul_f32_e32 v16, v6, v196
	v_mul_f32_e32 v16, v37, v16
	v_mul_f32_e32 v4, v6, v4
	v_cvt_pk_bf16_f32 v16, v16, v83
	s_waitcnt vmcnt(0)
	v_mul_f32_e32 v4, v61, v4
	ds_write_b16 v174, v16 offset:4624
	v_mul_f32_e32 v16, v6, v195
	v_cvt_pk_bf16_f32 v4, v4, v83
	v_mul_f32_e32 v16, v38, v16
	ds_write_b16 v174, v4 offset:6800
	v_mul_f32_e32 v4, v6, v165
	v_cvt_pk_bf16_f32 v16, v16, v83
	v_mul_f32_e32 v4, v62, v4
	ds_write_b16 v174, v16 offset:4896
	v_mul_f32_e32 v16, v6, v194
	v_cvt_pk_bf16_f32 v4, v4, v83
	v_mul_f32_e32 v16, v39, v16
	ds_write_b16 v174, v4 offset:7072
	v_mul_f32_e32 v4, v6, v164
	v_cvt_pk_bf16_f32 v16, v16, v83
	v_mul_f32_e32 v4, v63, v4
	ds_write_b16 v174, v16 offset:5168
	v_mul_f32_e32 v16, v6, v193
	v_cvt_pk_bf16_f32 v4, v4, v83
	v_mul_f32_e32 v16, v32, v16
	ds_write_b16 v174, v4 offset:7344
	v_mul_f32_e32 v4, v6, v167
	v_cvt_pk_bf16_f32 v16, v16, v83
	v_mul_f32_e32 v4, v52, v4
	ds_write_b16 v174, v16 offset:5440
	v_mul_f32_e32 v16, v6, v192
	v_cvt_pk_bf16_f32 v4, v4, v83
	v_mul_f32_e32 v16, v33, v16
	ds_write_b16 v174, v4 offset:7616
	v_mul_f32_e32 v4, v6, v166
	v_cvt_pk_bf16_f32 v16, v16, v83
	v_mul_f32_e32 v4, v53, v4
	ds_write_b16 v174, v16 offset:5712
	v_mul_f32_e32 v16, v6, v191
	v_cvt_pk_bf16_f32 v4, v4, v83
	v_mul_f32_e32 v16, v34, v16
	ds_write_b16 v174, v4 offset:7888
	v_mul_f32_e32 v4, v6, v179
	v_cvt_pk_bf16_f32 v16, v16, v83
	v_mul_f32_e32 v4, v54, v4
	ds_write_b16 v174, v16 offset:5984
	v_mul_f32_e32 v16, v6, v190
	v_cvt_pk_bf16_f32 v4, v4, v83
	v_mul_f32_e32 v16, v35, v16
	v_mul_f32_e32 v5, v6, v5
	ds_write_b16 v174, v4 offset:8160
	v_mul_f32_e32 v4, v6, v178
	v_cvt_pk_bf16_f32 v16, v16, v83
	v_mul_f32_e32 v5, v60, v5
	v_mul_f32_e32 v4, v55, v4
	ds_write_b16 v174, v16 offset:6256
	v_cvt_pk_bf16_f32 v5, v5, v83
	ds_write_b16 v174, v5 offset:6528
	v_cvt_pk_bf16_f32 v4, v4, v83
	ds_write_b16 v174, v4 offset:8432
	s_waitcnt lgkmcnt(0)
	s_barrier
; __device__ __forceinline__ float bf_lo(unsigned w) { return __uint_as_float(w << 16); }
; __device__ __forceinline__ float bf_hi(unsigned w) { return __uint_as_float(w & 0xffff0000u); }
; #define LAS __attribute__((address_space(3)))
; __device__ __forceinline__ unsigned cvt_pk_nv(float lo, float hi) { unsigned r; asm("v_cvt_pk_bf16_f32 %0, %1, %2" : "=v"(r) : "v"(lo), "v"(hi)); return r; }
; __device__ __forceinline__ void gmlp_tile(const Ctx& C, int T, LAS unsigned char* lds, int wave, int lane, int tid) {
;     ...
; #pragma unroll
;         for (int dbi = 0; dbi < 2; ++dbi) {
;             const int db = 2 * dh + dbi;
;             v16f acc;
; #pragma unroll
;             for (int r = 0; r < 16; ++r) acc[r] = 0.f;
; #pragma unroll
;             for (int ks = 0; ks < 8; ++ks) {
;                 const bfx8 va = *(const LAS bfx8*)(VT + (32 * db + tl) * VT_STRIDE + 16 * ks + 8 * hh);
;                 acc = __builtin_amdgcn_mfma_f32_32x32x16_bf16(va, wf[ks], acc, 0, 0, 0);
;             }
; #pragma unroll
;             for (int rg = 0; rg < 4; ++rg) {
;                 const v2u u2 = uw[dbi][rg];
;                 const float o0 = bf_lo(u2.x) * (acc[4 * rg + 0] + bias), o1 = bf_hi(u2.x) * (acc[4 * rg + 1] + bias);
;                 const float o2 = bf_lo(u2.y) * (acc[4 * rg + 2] + bias), o3 = bf_hi(u2.y) * (acc[4 * rg + 3] + bias);
;                 ssq += (o0 * o0 + o1 * o1) + (o2 * o2 + o3 * o3);
;                 outp[h][dbi][2 * rg] = cvt_pk_nv(o0, o1); outp[h][dbi][2 * rg + 1] = cvt_pk_nv(o2, o3);
;             }
	ds_read_b128 v[16:19], v102
	v_add_f32_e32 v4, v163, v7
	v_mul_f32_e32 v32, v4, v119
	v_mul_f32_e32 v4, v118, v118
	v_mul_f32_e32 v5, v32, v32
	v_fmac_f32_e32 v4, v181, v181
	v_fmac_f32_e32 v5, v189, v189
	v_add_f32_e32 v33, v4, v5
	ds_read_b128 v[4:7], v102 offset:32
	s_waitcnt lgkmcnt(1)
	v_mfma_f32_32x32x16_bf16 v[16:31], v[16:19], v[0:3], 0
	ds_read_b128 v[36:39], v102 offset:64
	v_lshlrev_b32_e32 v34, 16, v116
	v_mul_f32_e32 v34, v8, v34
	v_and_b32_e32 v8, 0xffff0000, v117
	v_add_f32_e32 v33, v33, v180
	ds_read_b128 v[60:63], v102 offset:8768
	v_cvt_pk_bf16_f32 v35, v181, v118
	s_waitcnt lgkmcnt(2)
	v_mfma_f32_32x32x16_bf16 v[16:31], v[4:7], v[72:75], v[16:31]
	v_and_b32_e32 v4, 0xffff0000, v116
	v_add_f32_e32 v5, v163, v9
	v_mul_f32_e32 v52, v5, v4
	v_lshlrev_b32_e32 v4, 16, v117
	v_add_f32_e32 v5, v163, v10
	v_mul_f32_e32 v53, v5, v4
	ds_read_b128 v[4:7], v102 offset:96
	s_waitcnt lgkmcnt(2)
	v_mfma_f32_32x32x16_bf16 v[16:31], v[36:39], v[68:71], v[16:31]
	v_add_f32_e32 v9, v163, v11
	v_mul_f32_e32 v37, v9, v8
	ds_read_b128 v[8:11], v102 offset:128
	v_mul_f32_e32 v36, v52, v52
	v_mul_f32_e32 v38, v37, v37
	v_fmac_f32_e32 v36, v34, v34
	v_fmac_f32_e32 v38, v53, v53
	s_waitcnt lgkmcnt(1)
	v_mfma_f32_32x32x16_bf16 v[16:31], v[4:7], v[64:67], v[16:31]
	v_add_f32_e32 v4, v36, v38
	v_add_f32_e32 v38, v4, v33
	ds_read_b128 v[4:7], v102 offset:160
	v_cvt_pk_bf16_f32 v36, v34, v52
	v_lshlrev_b32_e32 v34, 16, v112
	v_cvt_pk_bf16_f32 v33, v53, v37
	ds_read_b128 v[52:55], v102 offset:8736
	s_waitcnt lgkmcnt(2)
	v_mfma_f32_32x32x16_bf16 v[16:31], v[8:11], v[56:59], v[16:31]
	v_add_f32_e32 v8, v163, v12
	v_mul_f32_e32 v12, v8, v34
	v_and_b32_e32 v8, 0xffff0000, v112
	v_add_f32_e32 v9, v163, v13
	v_mul_f32_e32 v13, v9, v8
	ds_read_b128 v[8:11], v102 offset:192
	v_lshlrev_b32_e32 v34, 16, v113
	s_waitcnt lgkmcnt(2)
	v_mfma_f32_32x32x16_bf16 v[16:31], v[4:7], v[48:51], v[16:31]
	v_add_f32_e32 v4, v163, v14
	v_mul_f32_e32 v14, v4, v34
	v_and_b32_e32 v4, 0xffff0000, v113
	v_add_f32_e32 v5, v163, v15
	v_mul_f32_e32 v15, v5, v4
	ds_read_b128 v[4:7], v102 offset:224
	v_mul_f32_e32 v34, v13, v13
	s_waitcnt lgkmcnt(1)
	v_mfma_f32_32x32x16_bf16 v[16:31], v[8:11], v[44:47], v[16:31]
	v_mul_f32_e32 v8, v15, v15
	v_fmac_f32_e32 v34, v12, v12
	v_fmac_f32_e32 v8, v14, v14
	v_add_f32_e32 v8, v34, v8
	v_add_f32_e32 v8, v8, v38
	v_cvt_pk_bf16_f32 v37, v12, v13
	v_cvt_pk_bf16_f32 v34, v14, v15
	s_waitcnt lgkmcnt(0)
	v_mfma_f32_32x32x16_bf16 v[16:31], v[4:7], v[40:43], v[16:31]
	v_lshlrev_b32_e32 v4, 16, v122
	v_and_b32_e32 v39, 0xffff0000, v115
	v_cvt_pk_bf16_f32 v32, v189, v32
	s_nop 9
	v_add_f32_e32 v5, v156, v16
	v_mul_f32_e32 v4, v5, v4
	v_and_b32_e32 v5, 0xffff0000, v122
	v_add_f32_e32 v6, v156, v17
	v_mul_f32_e32 v5, v6, v5
	v_lshlrev_b32_e32 v6, 16, v123
	v_add_f32_e32 v7, v156, v18
	v_mul_f32_e32 v6, v7, v6
	v_and_b32_e32 v7, 0xffff0000, v123
	v_add_f32_e32 v9, v156, v19
	v_mul_f32_e32 v7, v9, v7
	v_mul_f32_e32 v9, v5, v5
	v_fmac_f32_e32 v9, v4, v4
	v_cvt_pk_bf16_f32 v17, v4, v5
	v_lshlrev_b32_e32 v4, 16, v120
	v_add_f32_e32 v5, v156, v20
	v_mul_f32_e32 v19, v5, v4
	v_and_b32_e32 v4, 0xffff0000, v120
	v_add_f32_e32 v5, v156, v21
	v_mul_f32_e32 v10, v7, v7
	v_mul_f32_e32 v20, v5, v4
	v_lshlrev_b32_e32 v4, 16, v121
	v_add_f32_e32 v5, v156, v22
	v_fmac_f32_e32 v10, v6, v6
	v_cvt_pk_bf16_f32 v16, v6, v7
	v_mul_f32_e32 v21, v5, v4
	ds_read_b128 v[4:7], v102 offset:8704
	v_add_f32_e32 v9, v9, v10
	v_add_f32_e32 v18, v8, v9
	v_and_b32_e32 v8, 0xffff0000, v121
	v_add_f32_e32 v9, v156, v23
	v_mul_f32_e32 v22, v9, v8
	v_mul_f32_e32 v8, v20, v20
	v_mul_f32_e32 v9, v22, v22
	v_fmac_f32_e32 v8, v19, v19
	v_fmac_f32_e32 v9, v21, v21
	v_add_f32_e32 v23, v8, v9
	s_waitcnt lgkmcnt(0)
	v_mfma_f32_32x32x16_bf16 v[0:15], v[4:7], v[0:3], 0
	v_add_f32_e32 v38, v23, v18
	v_cvt_pk_bf16_f32 v20, v19, v20
	v_cvt_pk_bf16_f32 v18, v21, v22
	v_lshlrev_b32_e32 v19, 16, v114
	v_add_f32_e32 v21, v156, v24
	v_mul_f32_e32 v19, v21, v19
	v_and_b32_e32 v21, 0xffff0000, v114
	v_mfma_f32_32x32x16_bf16 v[0:15], v[52:55], v[72:75], v[0:15]
	v_add_f32_e32 v22, v156, v25
	v_mul_f32_e32 v21, v22, v21
	v_lshlrev_b32_e32 v22, 16, v115
	v_add_f32_e32 v23, v156, v26
	v_mul_f32_e32 v26, v23, v22
	ds_read_b128 v[22:25], v102 offset:8800
	ds_read_b128 v[52:55], v102 offset:8832
	v_mfma_f32_32x32x16_bf16 v[0:15], v[60:63], v[68:71], v[0:15]
	v_add_f32_e32 v27, v156, v27
	v_mul_f32_e32 v27, v27, v39
	v_mul_f32_e32 v39, v21, v21
	v_mul_f32_e32 v60, v27, v27
	v_fmac_f32_e32 v39, v19, v19
	v_fmac_f32_e32 v60, v26, v26
	v_cvt_pk_bf16_f32 v21, v19, v21
	s_waitcnt lgkmcnt(1)
; __device__ __forceinline__ float bf_lo(unsigned w) { return __uint_as_float(w << 16); }
; __device__ __forceinline__ float bf_hi(unsigned w) { return __uint_as_float(w & 0xffff0000u); }
; #define LAS __attribute__((address_space(3)))
; __device__ __forceinline__ unsigned cvt_pk_nv(float lo, float hi) { unsigned r; asm("v_cvt_pk_bf16_f32 %0, %1, %2" : "=v"(r) : "v"(lo), "v"(hi)); return r; }
; __device__ __forceinline__ void gmlp_tile(const Ctx& C, int T, LAS unsigned char* lds, int wave, int lane, int tid) {
;     ...
; #pragma unroll
;         for (int dbi = 0; dbi < 2; ++dbi) {
;             const int db = 2 * dh + dbi;
;             v16f acc;
; #pragma unroll
;             for (int r = 0; r < 16; ++r) acc[r] = 0.f;
; #pragma unroll
;             for (int ks = 0; ks < 8; ++ks) {
;                 const bfx8 va = *(const LAS bfx8*)(VT + (32 * db + tl) * VT_STRIDE + 16 * ks + 8 * hh);
;                 acc = __builtin_amdgcn_mfma_f32_32x32x16_bf16(va, wf[ks], acc, 0, 0, 0);
;             }
; #pragma unroll
;             for (int rg = 0; rg < 4; ++rg) {
;                 const v2u u2 = uw[dbi][rg];
;                 const float o0 = bf_lo(u2.x) * (acc[4 * rg + 0] + bias), o1 = bf_hi(u2.x) * (acc[4 * rg + 1] + bias);
;                 const float o2 = bf_lo(u2.y) * (acc[4 * rg + 2] + bias), o3 = bf_hi(u2.y) * (acc[4 * rg + 3] + bias);
;                 ssq += (o0 * o0 + o1 * o1) + (o2 * o2 + o3 * o3);
;                 outp[h][dbi][2 * rg] = cvt_pk_nv(o0, o1); outp[h][dbi][2 * rg + 1] = cvt_pk_nv(o2, o3);
;             }
;         }
;     }
;     ssq += __shfl_xor(ssq, 32);
;     if (hh == 0) SSQ[t * 2 + dh] = ssq;
	v_mfma_f32_32x32x16_bf16 v[0:15], v[22:25], v[64:67], v[0:15]
	v_add_f32_e32 v22, v39, v60
	v_add_f32_e32 v38, v22, v38
	ds_read_b128 v[22:25], v102 offset:8864
	v_cvt_pk_bf16_f32 v19, v26, v27
	v_lshlrev_b32_e32 v26, 16, v110
	v_add_f32_e32 v27, v156, v28
	v_mul_f32_e32 v39, v27, v26
	s_waitcnt lgkmcnt(1)
	v_mfma_f32_32x32x16_bf16 v[0:15], v[52:55], v[56:59], v[0:15]
	v_and_b32_e32 v26, 0xffff0000, v110
	v_add_f32_e32 v27, v156, v29
	v_mul_f32_e32 v52, v27, v26
	ds_read_b128 v[26:29], v102 offset:8896
	v_lshlrev_b32_e32 v53, 16, v111
	s_waitcnt lgkmcnt(1)
	v_mfma_f32_32x32x16_bf16 v[0:15], v[22:25], v[48:51], v[0:15]
	ds_read_b128 v[48:51], v102 offset:8928
	v_and_b32_e32 v23, 0xffff0000, v111
	v_add_f32_e32 v24, v156, v31
	v_add_f32_e32 v22, v156, v30
	v_mul_f32_e32 v24, v24, v23
	v_mul_f32_e32 v22, v22, v53
	v_mul_f32_e32 v25, v24, v24
	s_waitcnt lgkmcnt(1)
	v_mfma_f32_32x32x16_bf16 v[0:15], v[26:29], v[44:47], v[0:15]
	v_fmac_f32_e32 v25, v22, v22
	v_cvt_pk_bf16_f32 v22, v22, v24
	v_lshlrev_b32_e32 v24, 16, v108
	v_mul_f32_e32 v23, v52, v52
	v_fmac_f32_e32 v23, v39, v39
	v_add_f32_e32 v23, v23, v25
	v_add_f32_e32 v25, v23, v38
	s_waitcnt lgkmcnt(0)
	v_mfma_f32_32x32x16_bf16 v[0:15], v[48:51], v[40:43], v[0:15]
	v_cvt_pk_bf16_f32 v23, v39, v52
	s_nop 11
	v_add_f32_e32 v0, v156, v0
	v_mul_f32_e32 v0, v0, v24
	v_and_b32_e32 v24, 0xffff0000, v108
	v_add_f32_e32 v1, v156, v1
	v_mul_f32_e32 v1, v1, v24
	v_lshlrev_b32_e32 v24, 16, v109
	v_add_f32_e32 v2, v156, v2
	v_mul_f32_e32 v2, v2, v24
	v_and_b32_e32 v24, 0xffff0000, v109
	v_add_f32_e32 v3, v156, v3
	v_mul_f32_e32 v24, v3, v24
	v_mul_f32_e32 v3, v1, v1
	v_mul_f32_e32 v26, v24, v24
	v_fmac_f32_e32 v3, v0, v0
	v_fmac_f32_e32 v26, v2, v2
	v_add_f32_e32 v3, v3, v26
	v_add_f32_e32 v25, v25, v3
	v_cvt_pk_bf16_f32 v3, v0, v1
	v_lshlrev_b32_e32 v0, 16, v104
	v_add_f32_e32 v1, v156, v4
	v_mul_f32_e32 v0, v1, v0
	v_and_b32_e32 v1, 0xffff0000, v104
	v_add_f32_e32 v4, v156, v5
	v_mul_f32_e32 v1, v4, v1
	v_lshlrev_b32_e32 v4, 16, v105
	v_add_f32_e32 v5, v156, v6
	v_mul_f32_e32 v4, v5, v4
	v_and_b32_e32 v5, 0xffff0000, v105
	v_add_f32_e32 v6, v156, v7
	v_mul_f32_e32 v6, v6, v5
	v_mul_f32_e32 v5, v1, v1
	v_mul_f32_e32 v7, v6, v6
	v_fmac_f32_e32 v5, v0, v0
	v_fmac_f32_e32 v7, v4, v4
	v_add_f32_e32 v5, v5, v7
	v_add_f32_e32 v7, v5, v25
	v_cvt_pk_bf16_f32 v5, v0, v1
	v_lshlrev_b32_e32 v0, 16, v78
	v_add_f32_e32 v1, v156, v8
	v_cvt_pk_bf16_f32 v4, v4, v6
	v_mul_f32_e32 v0, v1, v0
	v_and_b32_e32 v1, 0xffff0000, v78
	v_add_f32_e32 v6, v156, v9
	v_mul_f32_e32 v1, v6, v1
	v_lshlrev_b32_e32 v6, 16, v79
	v_add_f32_e32 v8, v156, v10
	v_mul_f32_e32 v8, v8, v6
	v_and_b32_e32 v6, 0xffff0000, v79
	v_add_f32_e32 v9, v156, v11
	v_mul_f32_e32 v9, v9, v6
	v_mul_f32_e32 v6, v1, v1
	v_mul_f32_e32 v10, v9, v9
	v_fmac_f32_e32 v6, v0, v0
	v_fmac_f32_e32 v10, v8, v8
	v_add_f32_e32 v6, v6, v10
	v_add_f32_e32 v7, v6, v7
	v_cvt_pk_bf16_f32 v6, v0, v1
	v_lshlrev_b32_e32 v0, 16, v76
	v_add_f32_e32 v1, v156, v12
	v_mul_f32_e32 v0, v1, v0
	v_and_b32_e32 v1, 0xffff0000, v76
	v_add_f32_e32 v10, v156, v13
	v_mul_f32_e32 v11, v10, v1
	v_lshlrev_b32_e32 v1, 16, v77
	v_add_f32_e32 v10, v156, v14
	v_mul_f32_e32 v12, v10, v1
	v_and_b32_e32 v1, 0xffff0000, v77
	v_add_f32_e32 v10, v156, v15
	v_mul_f32_e32 v13, v10, v1
	v_mul_f32_e32 v1, v11, v11
	v_mul_f32_e32 v10, v13, v13
	v_fmac_f32_e32 v1, v0, v0
	v_fmac_f32_e32 v10, v12, v12
	v_add_f32_e32 v1, v1, v10
	v_add_f32_e32 v1, v1, v7
	ds_bpermute_b32 v10, v188, v1
	v_cvt_pk_bf16_f32 v9, v8, v9
	v_cvt_pk_bf16_f32 v8, v0, v11
	v_lshlrev_b32_e32 v0, 3, v132
	v_cvt_pk_bf16_f32 v2, v2, v24
	v_cvt_pk_bf16_f32 v7, v12, v13
	s_and_saveexec_b64 s[28:29], s[8:9]
	s_cbranch_execz .LBB0_601
	s_lshl_b32 s0, s13, 2
	s_add_i32 s0, s0, 0
	s_waitcnt lgkmcnt(0)
	v_add_f32_e32 v1, v1, v10
	v_add_u32_e32 v10, s0, v0
	ds_write_b32 v10, v1 offset:34816
